# G2 mid hook: gate reads of two neighbouring 16-row groups fetched as one dwordx4 per lane and separated with v_permlane16_swap (64 -> 32 lane-scattered loads per unit)
# speedup vs baseline: 1.0047x; 1.0047x over previous
.LBB0_1080:
	s_andn2_b64 vcc, exec, s[26:27]
	s_cbranch_vccnz .LBB0_1082
	v_mov_b32_e32 v0, v151
	s_movk_i32 s30, 0x1320
	s_nop 0
	v_mad_u64_u32 v[2:3], s[28:29], v0, s30, v[136:137]
	v_mov_b32_e32 v231, 0
	v_bfe_u32 v232, v186, 4, 1
	v_mul_u32_u24_e32 v232, 0x131fc, v232
	v_add_u32_e32 v2, v2, v232
	v_add_u32_e32 v230, s13, v2
	v_lshlrev_b64 v[232:233], 1, v[230:231]
	v_lshl_add_u64 v[198:199], s[4:5], 0, v[232:233]
	v_lshl_add_u64 v[202:203], s[8:9], 0, v[232:233]
	global_load_dwordx4 v[198:201], v[198:199], off
	global_load_dwordx4 v[202:205], v[202:203], off
	v_add_u32_e32 v230, s56, v2
	v_lshlrev_b64 v[232:233], 1, v[230:231]
	v_lshl_add_u64 v[206:207], s[4:5], 0, v[232:233]
	v_lshl_add_u64 v[210:211], s[8:9], 0, v[232:233]
	global_load_dwordx4 v[206:209], v[206:207], off
	global_load_dwordx4 v[210:213], v[210:211], off
	v_add_u32_e32 v230, s57, v2
	v_lshlrev_b64 v[232:233], 1, v[230:231]
	v_lshl_add_u64 v[214:215], s[4:5], 0, v[232:233]
	v_lshl_add_u64 v[218:219], s[8:9], 0, v[232:233]
	global_load_dwordx4 v[214:217], v[214:215], off
	global_load_dwordx4 v[218:221], v[218:219], off
	v_add_u32_e32 v230, s58, v2
	v_lshlrev_b64 v[232:233], 1, v[230:231]
	v_lshl_add_u64 v[222:223], s[4:5], 0, v[232:233]
	v_lshl_add_u64 v[226:227], s[8:9], 0, v[232:233]
	global_load_dwordx4 v[222:225], v[222:223], off
	global_load_dwordx4 v[226:229], v[226:227], off
	s_waitcnt vmcnt(0)
	v_permlane16_swap_b32_e32 v198, v200
	v_permlane16_swap_b32_e32 v199, v201
	v_permlane16_swap_b32_e32 v202, v204
	v_permlane16_swap_b32_e32 v203, v205
	v_permlane16_swap_b32_e32 v206, v208
	v_permlane16_swap_b32_e32 v207, v209
	v_permlane16_swap_b32_e32 v210, v212
	v_permlane16_swap_b32_e32 v211, v213
	v_permlane16_swap_b32_e32 v214, v216
	v_permlane16_swap_b32_e32 v215, v217
	v_permlane16_swap_b32_e32 v218, v220
	v_permlane16_swap_b32_e32 v219, v221
	v_permlane16_swap_b32_e32 v222, v224
	v_permlane16_swap_b32_e32 v223, v225
	v_permlane16_swap_b32_e32 v226, v228
	v_permlane16_swap_b32_e32 v227, v229
	s_nop 1
	v_lshlrev_b32_e32 v0, 16, v202
	v_mul_f32_e32 v0, 0xbfb8aa3b, v0
	v_exp_f32_e32 v0, v0
	s_nop 0
	v_min_f32_e32 v168, 0x7149f2ca, v0
	v_lshlrev_b32_e32 v0, 16, v198
	v_mul_f32_e32 v0, 0xbfb8aa3b, v0
	v_exp_f32_e32 v0, v0
	s_nop 0
	v_min_f32_e32 v0, 0x7149f2ca, v0
	v_add_f32_e32 v0, 1.0, v0
	v_rcp_f32_e32 v170, v0
	v_and_b32_e32 v0, 0xffff0000, v202
	v_mul_f32_e32 v0, 0xbfb8aa3b, v0
	v_exp_f32_e32 v0, v0
	s_nop 0
	v_min_f32_e32 v169, 0x7149f2ca, v0
	v_and_b32_e32 v0, 0xffff0000, v198
	v_mul_f32_e32 v0, 0xbfb8aa3b, v0
	v_exp_f32_e32 v0, v0
	v_add_f32_e32 v168, 1.0, v168
	v_add_f32_e32 v169, 1.0, v169
	v_min_f32_e32 v0, 0x7149f2ca, v0
	v_add_f32_e32 v0, 1.0, v0
	v_rcp_f32_e32 v171, v0
	v_lshlrev_b32_e32 v0, 16, v203
	v_mul_f32_e32 v0, 0xbfb8aa3b, v0
	v_exp_f32_e32 v0, v0
	v_mul_f32_e32 v168, v168, v170
	v_mul_f32_e32 v169, v169, v171
	v_min_f32_e32 v146, 0x7149f2ca, v0
	v_lshlrev_b32_e32 v0, 16, v199
	v_mul_f32_e32 v0, 0xbfb8aa3b, v0
	v_exp_f32_e32 v0, v0
	v_mul_f32_e32 v128, v128, v168
	v_mul_f32_e32 v129, v129, v169
	v_min_f32_e32 v0, 0x7149f2ca, v0
	v_add_f32_e32 v0, 1.0, v0
	v_rcp_f32_e32 v166, v0
	v_and_b32_e32 v0, 0xffff0000, v203
	v_mul_f32_e32 v0, 0xbfb8aa3b, v0
	v_exp_f32_e32 v0, v0
	s_nop 0
	v_min_f32_e32 v147, 0x7149f2ca, v0
	v_and_b32_e32 v0, 0xffff0000, v199
	v_mul_f32_e32 v0, 0xbfb8aa3b, v0
	v_exp_f32_e32 v0, v0
	v_add_f32_e32 v146, 1.0, v146
	v_add_f32_e32 v147, 1.0, v147
	v_min_f32_e32 v0, 0x7149f2ca, v0
	v_add_f32_e32 v0, 1.0, v0
	v_rcp_f32_e32 v167, v0
	s_nop 0
	v_mul_f32_e32 v146, v146, v166
	v_mul_f32_e32 v147, v147, v167
	s_nop 0
	v_mul_f32_e32 v130, v130, v146
	v_mul_f32_e32 v131, v131, v147
	s_nop 0
	s_nop 0
	s_nop 0
	s_waitcnt vmcnt(4)
	v_lshlrev_b32_e32 v0, 16, v210
	v_mul_f32_e32 v0, 0xbfb8aa3b, v0
	v_exp_f32_e32 v0, v0
	s_nop 0
	v_min_f32_e32 v168, 0x7149f2ca, v0
	v_lshlrev_b32_e32 v0, 16, v206
	v_mul_f32_e32 v0, 0xbfb8aa3b, v0
	v_exp_f32_e32 v0, v0
	s_nop 0
	v_min_f32_e32 v0, 0x7149f2ca, v0
	v_add_f32_e32 v0, 1.0, v0
	v_rcp_f32_e32 v170, v0
	v_and_b32_e32 v0, 0xffff0000, v210
	v_mul_f32_e32 v0, 0xbfb8aa3b, v0
	v_exp_f32_e32 v0, v0
	s_nop 0
	v_min_f32_e32 v169, 0x7149f2ca, v0
	v_and_b32_e32 v0, 0xffff0000, v206
	v_mul_f32_e32 v0, 0xbfb8aa3b, v0
	v_exp_f32_e32 v0, v0
	v_add_f32_e32 v168, 1.0, v168
	v_add_f32_e32 v169, 1.0, v169
	v_min_f32_e32 v0, 0x7149f2ca, v0
	v_add_f32_e32 v0, 1.0, v0
	v_rcp_f32_e32 v171, v0
	v_lshlrev_b32_e32 v0, 16, v211
	v_mul_f32_e32 v0, 0xbfb8aa3b, v0
	v_exp_f32_e32 v0, v0
	v_mul_f32_e32 v168, v168, v170
	v_mul_f32_e32 v169, v169, v171
	v_min_f32_e32 v146, 0x7149f2ca, v0
	v_lshlrev_b32_e32 v0, 16, v207
	v_mul_f32_e32 v0, 0xbfb8aa3b, v0
	v_exp_f32_e32 v0, v0
	v_mul_f32_e32 v124, v124, v168
	v_mul_f32_e32 v125, v125, v169
	v_min_f32_e32 v0, 0x7149f2ca, v0
	v_add_f32_e32 v0, 1.0, v0
	v_rcp_f32_e32 v166, v0
	v_and_b32_e32 v0, 0xffff0000, v211
	v_mul_f32_e32 v0, 0xbfb8aa3b, v0
	v_exp_f32_e32 v0, v0
	s_nop 0
	v_min_f32_e32 v147, 0x7149f2ca, v0
	v_and_b32_e32 v0, 0xffff0000, v207
	v_mul_f32_e32 v0, 0xbfb8aa3b, v0
	v_exp_f32_e32 v0, v0
	v_add_f32_e32 v146, 1.0, v146
	v_add_f32_e32 v147, 1.0, v147
	v_min_f32_e32 v0, 0x7149f2ca, v0
	v_add_f32_e32 v0, 1.0, v0
	v_rcp_f32_e32 v167, v0
	s_nop 0
	v_mul_f32_e32 v146, v146, v166
	v_mul_f32_e32 v147, v147, v167
	s_nop 0
	v_mul_f32_e32 v126, v126, v146
	v_mul_f32_e32 v127, v127, v147
	s_nop 0
	s_nop 0
	s_nop 0
	s_waitcnt vmcnt(2)
	v_lshlrev_b32_e32 v0, 16, v218
	v_mul_f32_e32 v0, 0xbfb8aa3b, v0
	v_exp_f32_e32 v0, v0
	s_nop 0
	v_min_f32_e32 v168, 0x7149f2ca, v0
	v_lshlrev_b32_e32 v0, 16, v214
	v_mul_f32_e32 v0, 0xbfb8aa3b, v0
	v_exp_f32_e32 v0, v0
	s_nop 0
	v_min_f32_e32 v0, 0x7149f2ca, v0
	v_add_f32_e32 v0, 1.0, v0
	v_rcp_f32_e32 v170, v0
	v_and_b32_e32 v0, 0xffff0000, v218
	v_mul_f32_e32 v0, 0xbfb8aa3b, v0
	v_exp_f32_e32 v0, v0
	s_nop 0
	v_min_f32_e32 v169, 0x7149f2ca, v0
	v_and_b32_e32 v0, 0xffff0000, v214
	v_mul_f32_e32 v0, 0xbfb8aa3b, v0
	v_exp_f32_e32 v0, v0
	v_add_f32_e32 v168, 1.0, v168
	v_add_f32_e32 v169, 1.0, v169
	v_min_f32_e32 v0, 0x7149f2ca, v0
	v_add_f32_e32 v0, 1.0, v0
	v_rcp_f32_e32 v171, v0
	v_lshlrev_b32_e32 v0, 16, v219
	v_mul_f32_e32 v0, 0xbfb8aa3b, v0
	v_exp_f32_e32 v0, v0
	v_mul_f32_e32 v168, v168, v170
	v_mul_f32_e32 v169, v169, v171
	v_min_f32_e32 v146, 0x7149f2ca, v0
	v_lshlrev_b32_e32 v0, 16, v215
	v_mul_f32_e32 v0, 0xbfb8aa3b, v0
	v_exp_f32_e32 v0, v0
	v_mul_f32_e32 v120, v120, v168
	v_mul_f32_e32 v121, v121, v169
	v_min_f32_e32 v0, 0x7149f2ca, v0
	v_add_f32_e32 v0, 1.0, v0
	v_rcp_f32_e32 v166, v0
	v_and_b32_e32 v0, 0xffff0000, v219
	v_mul_f32_e32 v0, 0xbfb8aa3b, v0
	v_exp_f32_e32 v0, v0
	s_nop 0
	v_min_f32_e32 v147, 0x7149f2ca, v0
	v_and_b32_e32 v0, 0xffff0000, v215
	v_mul_f32_e32 v0, 0xbfb8aa3b, v0
	v_exp_f32_e32 v0, v0
	v_add_f32_e32 v146, 1.0, v146
	v_add_f32_e32 v147, 1.0, v147
	v_min_f32_e32 v0, 0x7149f2ca, v0
	v_add_f32_e32 v0, 1.0, v0
	v_rcp_f32_e32 v167, v0
	s_nop 0
	s_nop 0
	v_mul_f32_e32 v146, v146, v166
	v_mul_f32_e32 v147, v147, v167
	s_nop 0
	v_mul_f32_e32 v122, v122, v146
	v_mul_f32_e32 v123, v123, v147
	s_nop 0
	s_nop 0
	s_waitcnt vmcnt(0)
	v_lshlrev_b32_e32 v0, 16, v226
	v_mul_f32_e32 v0, 0xbfb8aa3b, v0
	v_exp_f32_e32 v0, v0
	s_nop 0
	v_min_f32_e32 v166, 0x7149f2ca, v0
	v_lshlrev_b32_e32 v0, 16, v222
	v_mul_f32_e32 v0, 0xbfb8aa3b, v0
	v_exp_f32_e32 v0, v0
	s_nop 0
	v_min_f32_e32 v0, 0x7149f2ca, v0
	v_add_f32_e32 v0, 1.0, v0
	v_rcp_f32_e32 v168, v0
	v_and_b32_e32 v0, 0xffff0000, v226
	v_mul_f32_e32 v0, 0xbfb8aa3b, v0
	v_exp_f32_e32 v0, v0
	s_nop 0
	v_min_f32_e32 v167, 0x7149f2ca, v0
	v_and_b32_e32 v0, 0xffff0000, v222
	v_mul_f32_e32 v0, 0xbfb8aa3b, v0
	v_exp_f32_e32 v0, v0
	v_add_f32_e32 v166, 1.0, v166
	v_add_f32_e32 v167, 1.0, v167
	v_min_f32_e32 v0, 0x7149f2ca, v0
	v_add_f32_e32 v0, 1.0, v0
	v_rcp_f32_e32 v169, v0
	v_lshlrev_b32_e32 v0, 16, v227
	v_mul_f32_e32 v0, 0xbfb8aa3b, v0
	v_exp_f32_e32 v0, v0
	v_mul_f32_e32 v166, v166, v168
	v_mul_f32_e32 v167, v167, v169
	v_min_f32_e32 v2, 0x7149f2ca, v0
	v_lshlrev_b32_e32 v0, 16, v223
	v_mul_f32_e32 v0, 0xbfb8aa3b, v0
	v_exp_f32_e32 v0, v0
	v_mul_f32_e32 v116, v116, v166
	v_mul_f32_e32 v117, v117, v167
	v_min_f32_e32 v0, 0x7149f2ca, v0
	v_add_f32_e32 v0, 1.0, v0
	v_rcp_f32_e32 v146, v0
	v_and_b32_e32 v0, 0xffff0000, v227
	v_mul_f32_e32 v0, 0xbfb8aa3b, v0
	v_exp_f32_e32 v0, v0
	s_nop 0
	v_min_f32_e32 v3, 0x7149f2ca, v0
	v_and_b32_e32 v0, 0xffff0000, v223
	v_mul_f32_e32 v0, 0xbfb8aa3b, v0
	v_exp_f32_e32 v0, v0
	v_add_f32_e32 v2, 1.0, v2
	v_add_f32_e32 v3, 1.0, v3
	v_min_f32_e32 v0, 0x7149f2ca, v0
	v_add_f32_e32 v0, 1.0, v0
	v_rcp_f32_e32 v147, v0
	v_mov_b32_e32 v0, v152
	v_mul_f32_e32 v2, v2, v146
	v_mul_f32_e32 v3, v3, v147
	s_nop 0
	v_mul_f32_e32 v118, v118, v2
	v_mul_f32_e32 v119, v119, v3
	s_nop 0
	s_nop 0
	v_mad_u64_u32 v[2:3], s[28:29], v0, s30, v[136:137]
	v_lshlrev_b32_e32 v0, 16, v204
	v_mul_f32_e32 v0, 0xbfb8aa3b, v0
	v_exp_f32_e32 v0, v0
	s_nop 0
	v_min_f32_e32 v168, 0x7149f2ca, v0
	v_lshlrev_b32_e32 v0, 16, v200
	v_mul_f32_e32 v0, 0xbfb8aa3b, v0
	v_exp_f32_e32 v0, v0
	s_nop 0
	v_min_f32_e32 v0, 0x7149f2ca, v0
	v_add_f32_e32 v0, 1.0, v0
	v_rcp_f32_e32 v170, v0
	v_and_b32_e32 v0, 0xffff0000, v204
	v_mul_f32_e32 v0, 0xbfb8aa3b, v0
	v_exp_f32_e32 v0, v0
	s_nop 0
	v_min_f32_e32 v169, 0x7149f2ca, v0
	v_and_b32_e32 v0, 0xffff0000, v200
	v_mul_f32_e32 v0, 0xbfb8aa3b, v0
	v_exp_f32_e32 v0, v0
	v_add_f32_e32 v168, 1.0, v168
	v_add_f32_e32 v169, 1.0, v169
	v_min_f32_e32 v0, 0x7149f2ca, v0
	v_add_f32_e32 v0, 1.0, v0
	v_rcp_f32_e32 v171, v0
	v_lshlrev_b32_e32 v0, 16, v205
	v_mul_f32_e32 v0, 0xbfb8aa3b, v0
	v_exp_f32_e32 v0, v0
	v_mul_f32_e32 v168, v168, v170
	v_mul_f32_e32 v169, v169, v171
	v_min_f32_e32 v146, 0x7149f2ca, v0
	v_lshlrev_b32_e32 v0, 16, v201
	v_mul_f32_e32 v0, 0xbfb8aa3b, v0
	v_exp_f32_e32 v0, v0
	v_mul_f32_e32 v112, v112, v168
	v_mul_f32_e32 v113, v113, v169
	v_min_f32_e32 v0, 0x7149f2ca, v0
	v_add_f32_e32 v0, 1.0, v0
	v_rcp_f32_e32 v166, v0
	v_and_b32_e32 v0, 0xffff0000, v205
	v_mul_f32_e32 v0, 0xbfb8aa3b, v0
	v_exp_f32_e32 v0, v0
	s_nop 0
	v_min_f32_e32 v147, 0x7149f2ca, v0
	v_and_b32_e32 v0, 0xffff0000, v201
	v_mul_f32_e32 v0, 0xbfb8aa3b, v0
	v_exp_f32_e32 v0, v0
	v_add_f32_e32 v146, 1.0, v146
	v_add_f32_e32 v147, 1.0, v147
	v_min_f32_e32 v0, 0x7149f2ca, v0
	v_add_f32_e32 v0, 1.0, v0
	v_rcp_f32_e32 v167, v0
	s_nop 0
	v_mul_f32_e32 v146, v146, v166
	v_mul_f32_e32 v147, v147, v167
	s_nop 0
	v_mul_f32_e32 v114, v114, v146
	v_mul_f32_e32 v115, v115, v147
	s_nop 0
	s_nop 0
	s_nop 0
	s_waitcnt vmcnt(4)
	v_lshlrev_b32_e32 v0, 16, v212
	v_mul_f32_e32 v0, 0xbfb8aa3b, v0
	v_exp_f32_e32 v0, v0
	s_nop 0
	v_min_f32_e32 v168, 0x7149f2ca, v0
	v_lshlrev_b32_e32 v0, 16, v208
	v_mul_f32_e32 v0, 0xbfb8aa3b, v0
	v_exp_f32_e32 v0, v0
	s_nop 0
	v_min_f32_e32 v0, 0x7149f2ca, v0
	v_add_f32_e32 v0, 1.0, v0
	v_rcp_f32_e32 v170, v0
	v_and_b32_e32 v0, 0xffff0000, v212
	v_mul_f32_e32 v0, 0xbfb8aa3b, v0
	v_exp_f32_e32 v0, v0
	s_nop 0
	v_min_f32_e32 v169, 0x7149f2ca, v0
	v_and_b32_e32 v0, 0xffff0000, v208
	v_mul_f32_e32 v0, 0xbfb8aa3b, v0
	v_exp_f32_e32 v0, v0
	v_add_f32_e32 v168, 1.0, v168
	v_add_f32_e32 v169, 1.0, v169
	v_min_f32_e32 v0, 0x7149f2ca, v0
	v_add_f32_e32 v0, 1.0, v0
	v_rcp_f32_e32 v171, v0
	v_lshlrev_b32_e32 v0, 16, v213
	v_mul_f32_e32 v0, 0xbfb8aa3b, v0
	v_exp_f32_e32 v0, v0
	v_mul_f32_e32 v168, v168, v170
	v_mul_f32_e32 v169, v169, v171
	v_min_f32_e32 v146, 0x7149f2ca, v0
	v_lshlrev_b32_e32 v0, 16, v209
	v_mul_f32_e32 v0, 0xbfb8aa3b, v0
	v_exp_f32_e32 v0, v0
	v_mul_f32_e32 v108, v108, v168
	v_mul_f32_e32 v109, v109, v169
	v_min_f32_e32 v0, 0x7149f2ca, v0
	v_add_f32_e32 v0, 1.0, v0
	v_rcp_f32_e32 v166, v0
	v_and_b32_e32 v0, 0xffff0000, v213
	v_mul_f32_e32 v0, 0xbfb8aa3b, v0
	v_exp_f32_e32 v0, v0
	s_nop 0
	v_min_f32_e32 v147, 0x7149f2ca, v0
	v_and_b32_e32 v0, 0xffff0000, v209
	v_mul_f32_e32 v0, 0xbfb8aa3b, v0
	v_exp_f32_e32 v0, v0
	v_add_f32_e32 v146, 1.0, v146
	v_add_f32_e32 v147, 1.0, v147
	v_min_f32_e32 v0, 0x7149f2ca, v0
	v_add_f32_e32 v0, 1.0, v0
	v_rcp_f32_e32 v167, v0
	s_nop 0
	v_mul_f32_e32 v146, v146, v166
	v_mul_f32_e32 v147, v147, v167
	s_nop 0
	v_mul_f32_e32 v110, v110, v146
	v_mul_f32_e32 v111, v111, v147
	s_nop 0
	s_nop 0
	s_nop 0
	s_waitcnt vmcnt(2)
	v_lshlrev_b32_e32 v0, 16, v220
	v_mul_f32_e32 v0, 0xbfb8aa3b, v0
	v_exp_f32_e32 v0, v0
	s_nop 0
	v_min_f32_e32 v168, 0x7149f2ca, v0
	v_lshlrev_b32_e32 v0, 16, v216
	v_mul_f32_e32 v0, 0xbfb8aa3b, v0
	v_exp_f32_e32 v0, v0
	s_nop 0
	v_min_f32_e32 v0, 0x7149f2ca, v0
	v_add_f32_e32 v0, 1.0, v0
	v_rcp_f32_e32 v170, v0
	v_and_b32_e32 v0, 0xffff0000, v220
	v_mul_f32_e32 v0, 0xbfb8aa3b, v0
	v_exp_f32_e32 v0, v0
	s_nop 0
	v_min_f32_e32 v169, 0x7149f2ca, v0
	v_and_b32_e32 v0, 0xffff0000, v216
	v_mul_f32_e32 v0, 0xbfb8aa3b, v0
	v_exp_f32_e32 v0, v0
	v_add_f32_e32 v168, 1.0, v168
	v_add_f32_e32 v169, 1.0, v169
	v_min_f32_e32 v0, 0x7149f2ca, v0
	v_add_f32_e32 v0, 1.0, v0
	v_rcp_f32_e32 v171, v0
	v_lshlrev_b32_e32 v0, 16, v221
	v_mul_f32_e32 v0, 0xbfb8aa3b, v0
	v_exp_f32_e32 v0, v0
	v_mul_f32_e32 v168, v168, v170
	v_mul_f32_e32 v169, v169, v171
	v_min_f32_e32 v146, 0x7149f2ca, v0
	v_lshlrev_b32_e32 v0, 16, v217
	v_mul_f32_e32 v0, 0xbfb8aa3b, v0
	v_exp_f32_e32 v0, v0
	v_mul_f32_e32 v104, v104, v168
	v_mul_f32_e32 v105, v105, v169
	v_min_f32_e32 v0, 0x7149f2ca, v0
	v_add_f32_e32 v0, 1.0, v0
	v_rcp_f32_e32 v166, v0
	v_and_b32_e32 v0, 0xffff0000, v221
	v_mul_f32_e32 v0, 0xbfb8aa3b, v0
	v_exp_f32_e32 v0, v0
	s_nop 0
	v_min_f32_e32 v147, 0x7149f2ca, v0
	v_and_b32_e32 v0, 0xffff0000, v217
	v_mul_f32_e32 v0, 0xbfb8aa3b, v0
	v_exp_f32_e32 v0, v0
	v_add_f32_e32 v146, 1.0, v146
	v_add_f32_e32 v147, 1.0, v147
	v_min_f32_e32 v0, 0x7149f2ca, v0
	v_add_f32_e32 v0, 1.0, v0
	v_rcp_f32_e32 v167, v0
	s_nop 0
	s_nop 0
	v_mul_f32_e32 v146, v146, v166
	v_mul_f32_e32 v147, v147, v167
	s_nop 0
	v_mul_f32_e32 v106, v106, v146
	v_mul_f32_e32 v107, v107, v147
	s_nop 0
	s_nop 0
	s_waitcnt vmcnt(0)
	v_lshlrev_b32_e32 v0, 16, v228
	v_mul_f32_e32 v0, 0xbfb8aa3b, v0
	v_exp_f32_e32 v0, v0
	s_nop 0
	v_min_f32_e32 v166, 0x7149f2ca, v0
	v_lshlrev_b32_e32 v0, 16, v224
	v_mul_f32_e32 v0, 0xbfb8aa3b, v0
	v_exp_f32_e32 v0, v0
	s_nop 0
	v_min_f32_e32 v0, 0x7149f2ca, v0
	v_add_f32_e32 v0, 1.0, v0
	v_rcp_f32_e32 v168, v0
	v_and_b32_e32 v0, 0xffff0000, v228
	v_mul_f32_e32 v0, 0xbfb8aa3b, v0
	v_exp_f32_e32 v0, v0
	s_nop 0
	v_min_f32_e32 v167, 0x7149f2ca, v0
	v_and_b32_e32 v0, 0xffff0000, v224
	v_mul_f32_e32 v0, 0xbfb8aa3b, v0
	v_exp_f32_e32 v0, v0
	v_add_f32_e32 v166, 1.0, v166
	v_add_f32_e32 v167, 1.0, v167
	v_min_f32_e32 v0, 0x7149f2ca, v0
	v_add_f32_e32 v0, 1.0, v0
	v_rcp_f32_e32 v169, v0
	v_lshlrev_b32_e32 v0, 16, v229
	v_mul_f32_e32 v0, 0xbfb8aa3b, v0
	v_exp_f32_e32 v0, v0
	v_mul_f32_e32 v166, v166, v168
	v_mul_f32_e32 v167, v167, v169
	v_min_f32_e32 v2, 0x7149f2ca, v0
	v_lshlrev_b32_e32 v0, 16, v225
	v_mul_f32_e32 v0, 0xbfb8aa3b, v0
	v_exp_f32_e32 v0, v0
	v_mul_f32_e32 v100, v100, v166
	v_mul_f32_e32 v101, v101, v167
	v_min_f32_e32 v0, 0x7149f2ca, v0
	v_add_f32_e32 v0, 1.0, v0
	v_rcp_f32_e32 v146, v0
	v_and_b32_e32 v0, 0xffff0000, v229
	v_mul_f32_e32 v0, 0xbfb8aa3b, v0
	v_exp_f32_e32 v0, v0
	s_nop 0
	v_min_f32_e32 v3, 0x7149f2ca, v0
	v_and_b32_e32 v0, 0xffff0000, v225
	v_mul_f32_e32 v0, 0xbfb8aa3b, v0
	v_exp_f32_e32 v0, v0
	v_add_f32_e32 v2, 1.0, v2
	v_add_f32_e32 v3, 1.0, v3
	v_min_f32_e32 v0, 0x7149f2ca, v0
	v_add_f32_e32 v0, 1.0, v0
	v_rcp_f32_e32 v147, v0
	v_mov_b32_e32 v0, v153
	v_mul_f32_e32 v2, v2, v146
	v_mul_f32_e32 v3, v3, v147
	s_nop 0
	v_mul_f32_e32 v102, v102, v2
	v_mul_f32_e32 v103, v103, v3
	s_nop 0
	s_nop 0
	v_mad_u64_u32 v[2:3], s[28:29], v0, s30, v[136:137]
	v_mov_b32_e32 v231, 0
	v_bfe_u32 v232, v186, 4, 1
	v_mul_u32_u24_e32 v232, 0x131fc, v232
	v_add_u32_e32 v2, v2, v232
	v_add_u32_e32 v230, s13, v2
	v_lshlrev_b64 v[232:233], 1, v[230:231]
	v_lshl_add_u64 v[198:199], s[4:5], 0, v[232:233]
	v_lshl_add_u64 v[202:203], s[8:9], 0, v[232:233]
	global_load_dwordx4 v[198:201], v[198:199], off
	global_load_dwordx4 v[202:205], v[202:203], off
	v_add_u32_e32 v230, s56, v2
	v_lshlrev_b64 v[232:233], 1, v[230:231]
	v_lshl_add_u64 v[206:207], s[4:5], 0, v[232:233]
	v_lshl_add_u64 v[210:211], s[8:9], 0, v[232:233]
	global_load_dwordx4 v[206:209], v[206:207], off
	global_load_dwordx4 v[210:213], v[210:211], off
	v_add_u32_e32 v230, s57, v2
	v_lshlrev_b64 v[232:233], 1, v[230:231]
	v_lshl_add_u64 v[214:215], s[4:5], 0, v[232:233]
	v_lshl_add_u64 v[218:219], s[8:9], 0, v[232:233]
	global_load_dwordx4 v[214:217], v[214:215], off
	global_load_dwordx4 v[218:221], v[218:219], off
	v_add_u32_e32 v230, s58, v2
	v_lshlrev_b64 v[232:233], 1, v[230:231]
	v_lshl_add_u64 v[222:223], s[4:5], 0, v[232:233]
	v_lshl_add_u64 v[226:227], s[8:9], 0, v[232:233]
	global_load_dwordx4 v[222:225], v[222:223], off
	global_load_dwordx4 v[226:229], v[226:227], off
	s_waitcnt vmcnt(0)
	v_permlane16_swap_b32_e32 v198, v200
	v_permlane16_swap_b32_e32 v199, v201
	v_permlane16_swap_b32_e32 v202, v204
	v_permlane16_swap_b32_e32 v203, v205
	v_permlane16_swap_b32_e32 v206, v208
	v_permlane16_swap_b32_e32 v207, v209
	v_permlane16_swap_b32_e32 v210, v212
	v_permlane16_swap_b32_e32 v211, v213
	v_permlane16_swap_b32_e32 v214, v216
	v_permlane16_swap_b32_e32 v215, v217
	v_permlane16_swap_b32_e32 v218, v220
	v_permlane16_swap_b32_e32 v219, v221
	v_permlane16_swap_b32_e32 v222, v224
	v_permlane16_swap_b32_e32 v223, v225
	v_permlane16_swap_b32_e32 v226, v228
	v_permlane16_swap_b32_e32 v227, v229
	s_nop 1
	v_lshlrev_b32_e32 v0, 16, v202
	v_mul_f32_e32 v0, 0xbfb8aa3b, v0
	v_exp_f32_e32 v0, v0
	s_nop 0
	v_min_f32_e32 v168, 0x7149f2ca, v0
	v_lshlrev_b32_e32 v0, 16, v198
	v_mul_f32_e32 v0, 0xbfb8aa3b, v0
	v_exp_f32_e32 v0, v0
	s_nop 0
	v_min_f32_e32 v0, 0x7149f2ca, v0
	v_add_f32_e32 v0, 1.0, v0
	v_rcp_f32_e32 v170, v0
	v_and_b32_e32 v0, 0xffff0000, v202
	v_mul_f32_e32 v0, 0xbfb8aa3b, v0
	v_exp_f32_e32 v0, v0
	s_nop 0
	v_min_f32_e32 v169, 0x7149f2ca, v0
	v_and_b32_e32 v0, 0xffff0000, v198
	v_mul_f32_e32 v0, 0xbfb8aa3b, v0
	v_exp_f32_e32 v0, v0
	v_add_f32_e32 v168, 1.0, v168
	v_add_f32_e32 v169, 1.0, v169
	v_min_f32_e32 v0, 0x7149f2ca, v0
	v_add_f32_e32 v0, 1.0, v0
	v_rcp_f32_e32 v171, v0
	v_lshlrev_b32_e32 v0, 16, v203
	v_mul_f32_e32 v0, 0xbfb8aa3b, v0
	v_exp_f32_e32 v0, v0
	v_mul_f32_e32 v168, v168, v170
	v_mul_f32_e32 v169, v169, v171
	v_min_f32_e32 v146, 0x7149f2ca, v0
	v_lshlrev_b32_e32 v0, 16, v199
	v_mul_f32_e32 v0, 0xbfb8aa3b, v0
	v_exp_f32_e32 v0, v0
	v_mul_f32_e32 v96, v96, v168
	v_mul_f32_e32 v97, v97, v169
	v_min_f32_e32 v0, 0x7149f2ca, v0
	v_add_f32_e32 v0, 1.0, v0
	v_rcp_f32_e32 v166, v0
	v_and_b32_e32 v0, 0xffff0000, v203
	v_mul_f32_e32 v0, 0xbfb8aa3b, v0
	v_exp_f32_e32 v0, v0
	s_nop 0
	v_min_f32_e32 v147, 0x7149f2ca, v0
	v_and_b32_e32 v0, 0xffff0000, v199
	v_mul_f32_e32 v0, 0xbfb8aa3b, v0
	v_exp_f32_e32 v0, v0
	v_add_f32_e32 v146, 1.0, v146
	v_add_f32_e32 v147, 1.0, v147
	v_min_f32_e32 v0, 0x7149f2ca, v0
	v_add_f32_e32 v0, 1.0, v0
	v_rcp_f32_e32 v167, v0
	s_nop 0
	v_mul_f32_e32 v146, v146, v166
	v_mul_f32_e32 v147, v147, v167
	s_nop 0
	v_mul_f32_e32 v98, v98, v146
	v_mul_f32_e32 v99, v99, v147
	s_nop 0
	s_nop 0
	s_nop 0
	s_waitcnt vmcnt(4)
	v_lshlrev_b32_e32 v0, 16, v210
	v_mul_f32_e32 v0, 0xbfb8aa3b, v0
	v_exp_f32_e32 v0, v0
	s_nop 0
	v_min_f32_e32 v168, 0x7149f2ca, v0
	v_lshlrev_b32_e32 v0, 16, v206
	v_mul_f32_e32 v0, 0xbfb8aa3b, v0
	v_exp_f32_e32 v0, v0
	s_nop 0
	v_min_f32_e32 v0, 0x7149f2ca, v0
	v_add_f32_e32 v0, 1.0, v0
	v_rcp_f32_e32 v170, v0
	v_and_b32_e32 v0, 0xffff0000, v210
	v_mul_f32_e32 v0, 0xbfb8aa3b, v0
	v_exp_f32_e32 v0, v0
	s_nop 0
	v_min_f32_e32 v169, 0x7149f2ca, v0
	v_and_b32_e32 v0, 0xffff0000, v206
	v_mul_f32_e32 v0, 0xbfb8aa3b, v0
	v_exp_f32_e32 v0, v0
	v_add_f32_e32 v168, 1.0, v168
	v_add_f32_e32 v169, 1.0, v169
	v_min_f32_e32 v0, 0x7149f2ca, v0
	v_add_f32_e32 v0, 1.0, v0
	v_rcp_f32_e32 v171, v0
	v_lshlrev_b32_e32 v0, 16, v211
	v_mul_f32_e32 v0, 0xbfb8aa3b, v0
	v_exp_f32_e32 v0, v0
	v_mul_f32_e32 v168, v168, v170
	v_mul_f32_e32 v169, v169, v171
	v_min_f32_e32 v146, 0x7149f2ca, v0
	v_lshlrev_b32_e32 v0, 16, v207
	v_mul_f32_e32 v0, 0xbfb8aa3b, v0
	v_exp_f32_e32 v0, v0
	v_mul_f32_e32 v92, v92, v168
	v_mul_f32_e32 v93, v93, v169
	v_min_f32_e32 v0, 0x7149f2ca, v0
	v_add_f32_e32 v0, 1.0, v0
	v_rcp_f32_e32 v166, v0
	v_and_b32_e32 v0, 0xffff0000, v211
	v_mul_f32_e32 v0, 0xbfb8aa3b, v0
	v_exp_f32_e32 v0, v0
	s_nop 0
	v_min_f32_e32 v147, 0x7149f2ca, v0
	v_and_b32_e32 v0, 0xffff0000, v207
	v_mul_f32_e32 v0, 0xbfb8aa3b, v0
	v_exp_f32_e32 v0, v0
	v_add_f32_e32 v146, 1.0, v146
	v_add_f32_e32 v147, 1.0, v147
	v_min_f32_e32 v0, 0x7149f2ca, v0
	v_add_f32_e32 v0, 1.0, v0
	v_rcp_f32_e32 v167, v0
	s_nop 0
	v_mul_f32_e32 v146, v146, v166
	v_mul_f32_e32 v147, v147, v167
	s_nop 0
	v_mul_f32_e32 v94, v94, v146
	v_mul_f32_e32 v95, v95, v147
	s_nop 0
	s_nop 0
	s_nop 0
	s_waitcnt vmcnt(2)
	v_lshlrev_b32_e32 v0, 16, v218
	v_mul_f32_e32 v0, 0xbfb8aa3b, v0
	v_exp_f32_e32 v0, v0
	s_nop 0
	v_min_f32_e32 v168, 0x7149f2ca, v0
	v_lshlrev_b32_e32 v0, 16, v214
	v_mul_f32_e32 v0, 0xbfb8aa3b, v0
	v_exp_f32_e32 v0, v0
	s_nop 0
	v_min_f32_e32 v0, 0x7149f2ca, v0
	v_add_f32_e32 v0, 1.0, v0
	v_rcp_f32_e32 v170, v0
	v_and_b32_e32 v0, 0xffff0000, v218
	v_mul_f32_e32 v0, 0xbfb8aa3b, v0
	v_exp_f32_e32 v0, v0
	s_nop 0
	v_min_f32_e32 v169, 0x7149f2ca, v0
	v_and_b32_e32 v0, 0xffff0000, v214
	v_mul_f32_e32 v0, 0xbfb8aa3b, v0
	v_exp_f32_e32 v0, v0
	v_add_f32_e32 v168, 1.0, v168
	v_add_f32_e32 v169, 1.0, v169
	v_min_f32_e32 v0, 0x7149f2ca, v0
	v_add_f32_e32 v0, 1.0, v0
	v_rcp_f32_e32 v171, v0
	v_lshlrev_b32_e32 v0, 16, v219
	v_mul_f32_e32 v0, 0xbfb8aa3b, v0
	v_exp_f32_e32 v0, v0
	v_mul_f32_e32 v168, v168, v170
	v_mul_f32_e32 v169, v169, v171
	v_min_f32_e32 v146, 0x7149f2ca, v0
	v_lshlrev_b32_e32 v0, 16, v215
	v_mul_f32_e32 v0, 0xbfb8aa3b, v0
	v_exp_f32_e32 v0, v0
	v_mul_f32_e32 v88, v88, v168
	v_mul_f32_e32 v89, v89, v169
	v_min_f32_e32 v0, 0x7149f2ca, v0
	v_add_f32_e32 v0, 1.0, v0
	v_rcp_f32_e32 v166, v0
	v_and_b32_e32 v0, 0xffff0000, v219
	v_mul_f32_e32 v0, 0xbfb8aa3b, v0
	v_exp_f32_e32 v0, v0
	s_nop 0
	v_min_f32_e32 v147, 0x7149f2ca, v0
	v_and_b32_e32 v0, 0xffff0000, v215
	v_mul_f32_e32 v0, 0xbfb8aa3b, v0
	v_exp_f32_e32 v0, v0
	v_add_f32_e32 v146, 1.0, v146
	v_add_f32_e32 v147, 1.0, v147
	v_min_f32_e32 v0, 0x7149f2ca, v0
	v_add_f32_e32 v0, 1.0, v0
	v_rcp_f32_e32 v167, v0
	s_nop 0
	s_nop 0
	v_mul_f32_e32 v146, v146, v166
	v_mul_f32_e32 v147, v147, v167
	s_nop 0
	v_mul_f32_e32 v90, v90, v146
	v_mul_f32_e32 v91, v91, v147
	s_nop 0
	s_nop 0
	s_waitcnt vmcnt(0)
	v_lshlrev_b32_e32 v0, 16, v226
	v_mul_f32_e32 v0, 0xbfb8aa3b, v0
	v_exp_f32_e32 v0, v0
	s_nop 0
	v_min_f32_e32 v166, 0x7149f2ca, v0
	v_lshlrev_b32_e32 v0, 16, v222
	v_mul_f32_e32 v0, 0xbfb8aa3b, v0
	v_exp_f32_e32 v0, v0
	s_nop 0
	v_min_f32_e32 v0, 0x7149f2ca, v0
	v_add_f32_e32 v0, 1.0, v0
	v_rcp_f32_e32 v168, v0
	v_and_b32_e32 v0, 0xffff0000, v226
	v_mul_f32_e32 v0, 0xbfb8aa3b, v0
	v_exp_f32_e32 v0, v0
	s_nop 0
	v_min_f32_e32 v167, 0x7149f2ca, v0
	v_and_b32_e32 v0, 0xffff0000, v222
	v_mul_f32_e32 v0, 0xbfb8aa3b, v0
	v_exp_f32_e32 v0, v0
	v_add_f32_e32 v166, 1.0, v166
	v_add_f32_e32 v167, 1.0, v167
	v_min_f32_e32 v0, 0x7149f2ca, v0
	v_add_f32_e32 v0, 1.0, v0
	v_rcp_f32_e32 v169, v0
	v_lshlrev_b32_e32 v0, 16, v227
	v_mul_f32_e32 v0, 0xbfb8aa3b, v0
	v_exp_f32_e32 v0, v0
	v_mul_f32_e32 v166, v166, v168
	v_mul_f32_e32 v167, v167, v169
	v_min_f32_e32 v2, 0x7149f2ca, v0
	v_lshlrev_b32_e32 v0, 16, v223
	v_mul_f32_e32 v0, 0xbfb8aa3b, v0
	v_exp_f32_e32 v0, v0
	v_mul_f32_e32 v84, v84, v166
	v_mul_f32_e32 v85, v85, v167
	v_min_f32_e32 v0, 0x7149f2ca, v0
	v_add_f32_e32 v0, 1.0, v0
	v_rcp_f32_e32 v146, v0
	v_and_b32_e32 v0, 0xffff0000, v227
	v_mul_f32_e32 v0, 0xbfb8aa3b, v0
	v_exp_f32_e32 v0, v0
	s_nop 0
	v_min_f32_e32 v3, 0x7149f2ca, v0
	v_and_b32_e32 v0, 0xffff0000, v223
	v_mul_f32_e32 v0, 0xbfb8aa3b, v0
	v_exp_f32_e32 v0, v0
	v_add_f32_e32 v2, 1.0, v2
	v_add_f32_e32 v3, 1.0, v3
	v_min_f32_e32 v0, 0x7149f2ca, v0
	v_add_f32_e32 v0, 1.0, v0
	v_rcp_f32_e32 v147, v0
	v_mov_b32_e32 v0, v154
	v_mul_f32_e32 v2, v2, v146
	v_mul_f32_e32 v3, v3, v147
	s_nop 0
	v_mul_f32_e32 v86, v86, v2
	v_mul_f32_e32 v87, v87, v3
	s_nop 0
	s_nop 0
	v_mad_u64_u32 v[2:3], s[28:29], v0, s30, v[136:137]
	v_lshlrev_b32_e32 v0, 16, v204
	v_mul_f32_e32 v0, 0xbfb8aa3b, v0
	v_exp_f32_e32 v0, v0
	s_nop 0
	v_min_f32_e32 v168, 0x7149f2ca, v0
	v_lshlrev_b32_e32 v0, 16, v200
	v_mul_f32_e32 v0, 0xbfb8aa3b, v0
	v_exp_f32_e32 v0, v0
	s_nop 0
	v_min_f32_e32 v0, 0x7149f2ca, v0
	v_add_f32_e32 v0, 1.0, v0
	v_rcp_f32_e32 v170, v0
	v_and_b32_e32 v0, 0xffff0000, v204
	v_mul_f32_e32 v0, 0xbfb8aa3b, v0
	v_exp_f32_e32 v0, v0
	s_nop 0
	v_min_f32_e32 v169, 0x7149f2ca, v0
	v_and_b32_e32 v0, 0xffff0000, v200
	v_mul_f32_e32 v0, 0xbfb8aa3b, v0
	v_exp_f32_e32 v0, v0
	v_add_f32_e32 v168, 1.0, v168
	v_add_f32_e32 v169, 1.0, v169
	v_min_f32_e32 v0, 0x7149f2ca, v0
	v_add_f32_e32 v0, 1.0, v0
	v_rcp_f32_e32 v171, v0
	v_lshlrev_b32_e32 v0, 16, v205
	v_mul_f32_e32 v0, 0xbfb8aa3b, v0
	v_exp_f32_e32 v0, v0
	v_mul_f32_e32 v168, v168, v170
	v_mul_f32_e32 v169, v169, v171
	v_min_f32_e32 v146, 0x7149f2ca, v0
	v_lshlrev_b32_e32 v0, 16, v201
	v_mul_f32_e32 v0, 0xbfb8aa3b, v0
	v_exp_f32_e32 v0, v0
	v_mul_f32_e32 v80, v80, v168
	v_mul_f32_e32 v81, v81, v169
	v_min_f32_e32 v0, 0x7149f2ca, v0
	v_add_f32_e32 v0, 1.0, v0
	v_rcp_f32_e32 v166, v0
	v_and_b32_e32 v0, 0xffff0000, v205
	v_mul_f32_e32 v0, 0xbfb8aa3b, v0
	v_exp_f32_e32 v0, v0
	s_nop 0
	v_min_f32_e32 v147, 0x7149f2ca, v0
	v_and_b32_e32 v0, 0xffff0000, v201
	v_mul_f32_e32 v0, 0xbfb8aa3b, v0
	v_exp_f32_e32 v0, v0
	v_add_f32_e32 v146, 1.0, v146
	v_add_f32_e32 v147, 1.0, v147
	v_min_f32_e32 v0, 0x7149f2ca, v0
	v_add_f32_e32 v0, 1.0, v0
	v_rcp_f32_e32 v167, v0
	s_nop 0
	v_mul_f32_e32 v146, v146, v166
	v_mul_f32_e32 v147, v147, v167
	s_nop 0
	v_mul_f32_e32 v82, v82, v146
	v_mul_f32_e32 v83, v83, v147
	s_nop 0
	s_nop 0
	s_nop 0
	s_waitcnt vmcnt(4)
	v_lshlrev_b32_e32 v0, 16, v212
	v_mul_f32_e32 v0, 0xbfb8aa3b, v0
	v_exp_f32_e32 v0, v0
	s_nop 0
	v_min_f32_e32 v168, 0x7149f2ca, v0
	v_lshlrev_b32_e32 v0, 16, v208
	v_mul_f32_e32 v0, 0xbfb8aa3b, v0
	v_exp_f32_e32 v0, v0
	s_nop 0
	v_min_f32_e32 v0, 0x7149f2ca, v0
	v_add_f32_e32 v0, 1.0, v0
	v_rcp_f32_e32 v170, v0
	v_and_b32_e32 v0, 0xffff0000, v212
	v_mul_f32_e32 v0, 0xbfb8aa3b, v0
	v_exp_f32_e32 v0, v0
	s_nop 0
	v_min_f32_e32 v169, 0x7149f2ca, v0
	v_and_b32_e32 v0, 0xffff0000, v208
	v_mul_f32_e32 v0, 0xbfb8aa3b, v0
	v_exp_f32_e32 v0, v0
	v_add_f32_e32 v168, 1.0, v168
	v_add_f32_e32 v169, 1.0, v169
	v_min_f32_e32 v0, 0x7149f2ca, v0
	v_add_f32_e32 v0, 1.0, v0
	v_rcp_f32_e32 v171, v0
	v_lshlrev_b32_e32 v0, 16, v213
	v_mul_f32_e32 v0, 0xbfb8aa3b, v0
	v_exp_f32_e32 v0, v0
	v_mul_f32_e32 v168, v168, v170
	v_mul_f32_e32 v169, v169, v171
	v_min_f32_e32 v146, 0x7149f2ca, v0
	v_lshlrev_b32_e32 v0, 16, v209
	v_mul_f32_e32 v0, 0xbfb8aa3b, v0
	v_exp_f32_e32 v0, v0
	v_mul_f32_e32 v76, v76, v168
	v_mul_f32_e32 v77, v77, v169
	v_min_f32_e32 v0, 0x7149f2ca, v0
	v_add_f32_e32 v0, 1.0, v0
	v_rcp_f32_e32 v166, v0
	v_and_b32_e32 v0, 0xffff0000, v213
	v_mul_f32_e32 v0, 0xbfb8aa3b, v0
	v_exp_f32_e32 v0, v0
	s_nop 0
	v_min_f32_e32 v147, 0x7149f2ca, v0
	v_and_b32_e32 v0, 0xffff0000, v209
	v_mul_f32_e32 v0, 0xbfb8aa3b, v0
	v_exp_f32_e32 v0, v0
	v_add_f32_e32 v146, 1.0, v146
	v_add_f32_e32 v147, 1.0, v147
	v_min_f32_e32 v0, 0x7149f2ca, v0
	v_add_f32_e32 v0, 1.0, v0
	v_rcp_f32_e32 v167, v0
	s_nop 0
	v_mul_f32_e32 v146, v146, v166
	v_mul_f32_e32 v147, v147, v167
	s_nop 0
	v_mul_f32_e32 v78, v78, v146
	v_mul_f32_e32 v79, v79, v147
	s_nop 0
	s_nop 0
	s_nop 0
	s_waitcnt vmcnt(2)
	v_lshlrev_b32_e32 v0, 16, v220
	v_mul_f32_e32 v0, 0xbfb8aa3b, v0
	v_exp_f32_e32 v0, v0
	s_nop 0
	v_min_f32_e32 v168, 0x7149f2ca, v0
	v_lshlrev_b32_e32 v0, 16, v216
	v_mul_f32_e32 v0, 0xbfb8aa3b, v0
	v_exp_f32_e32 v0, v0
	s_nop 0
	v_min_f32_e32 v0, 0x7149f2ca, v0
	v_add_f32_e32 v0, 1.0, v0
	v_rcp_f32_e32 v170, v0
	v_and_b32_e32 v0, 0xffff0000, v220
	v_mul_f32_e32 v0, 0xbfb8aa3b, v0
	v_exp_f32_e32 v0, v0
	s_nop 0
	v_min_f32_e32 v169, 0x7149f2ca, v0
	v_and_b32_e32 v0, 0xffff0000, v216
	v_mul_f32_e32 v0, 0xbfb8aa3b, v0
	v_exp_f32_e32 v0, v0
	v_add_f32_e32 v168, 1.0, v168
	v_add_f32_e32 v169, 1.0, v169
	v_min_f32_e32 v0, 0x7149f2ca, v0
	v_add_f32_e32 v0, 1.0, v0
	v_rcp_f32_e32 v171, v0
	v_lshlrev_b32_e32 v0, 16, v221
	v_mul_f32_e32 v0, 0xbfb8aa3b, v0
	v_exp_f32_e32 v0, v0
	v_mul_f32_e32 v168, v168, v170
	v_mul_f32_e32 v169, v169, v171
	v_min_f32_e32 v146, 0x7149f2ca, v0
	v_lshlrev_b32_e32 v0, 16, v217
	v_mul_f32_e32 v0, 0xbfb8aa3b, v0
	v_exp_f32_e32 v0, v0
	v_mul_f32_e32 v72, v72, v168
	v_mul_f32_e32 v73, v73, v169
	v_min_f32_e32 v0, 0x7149f2ca, v0
	v_add_f32_e32 v0, 1.0, v0
	v_rcp_f32_e32 v166, v0
	v_and_b32_e32 v0, 0xffff0000, v221
	v_mul_f32_e32 v0, 0xbfb8aa3b, v0
	v_exp_f32_e32 v0, v0
	s_nop 0
	v_min_f32_e32 v147, 0x7149f2ca, v0
	v_and_b32_e32 v0, 0xffff0000, v217
	v_mul_f32_e32 v0, 0xbfb8aa3b, v0
	v_exp_f32_e32 v0, v0
	v_add_f32_e32 v146, 1.0, v146
	v_add_f32_e32 v147, 1.0, v147
	v_min_f32_e32 v0, 0x7149f2ca, v0
	v_add_f32_e32 v0, 1.0, v0
	v_rcp_f32_e32 v167, v0
	s_nop 0
	s_nop 0
	v_mul_f32_e32 v146, v146, v166
	v_mul_f32_e32 v147, v147, v167
	s_nop 0
	v_mul_f32_e32 v74, v74, v146
	v_mul_f32_e32 v75, v75, v147
	s_nop 0
	s_nop 0
	s_waitcnt vmcnt(0)
	v_lshlrev_b32_e32 v0, 16, v228
	v_mul_f32_e32 v0, 0xbfb8aa3b, v0
	v_exp_f32_e32 v0, v0
	s_nop 0
	v_min_f32_e32 v166, 0x7149f2ca, v0
	v_lshlrev_b32_e32 v0, 16, v224
	v_mul_f32_e32 v0, 0xbfb8aa3b, v0
	v_exp_f32_e32 v0, v0
	s_nop 0
	v_min_f32_e32 v0, 0x7149f2ca, v0
	v_add_f32_e32 v0, 1.0, v0
	v_rcp_f32_e32 v168, v0
	v_and_b32_e32 v0, 0xffff0000, v228
	v_mul_f32_e32 v0, 0xbfb8aa3b, v0
	v_exp_f32_e32 v0, v0
	s_nop 0
	v_min_f32_e32 v167, 0x7149f2ca, v0
	v_and_b32_e32 v0, 0xffff0000, v224
	v_mul_f32_e32 v0, 0xbfb8aa3b, v0
	v_exp_f32_e32 v0, v0
	v_add_f32_e32 v166, 1.0, v166
	v_add_f32_e32 v167, 1.0, v167
	v_min_f32_e32 v0, 0x7149f2ca, v0
	v_add_f32_e32 v0, 1.0, v0
	v_rcp_f32_e32 v169, v0
	v_lshlrev_b32_e32 v0, 16, v229
	v_mul_f32_e32 v0, 0xbfb8aa3b, v0
	v_exp_f32_e32 v0, v0
	v_mul_f32_e32 v166, v166, v168
	v_mul_f32_e32 v167, v167, v169
	v_min_f32_e32 v2, 0x7149f2ca, v0
	v_lshlrev_b32_e32 v0, 16, v225
	v_mul_f32_e32 v0, 0xbfb8aa3b, v0
	v_exp_f32_e32 v0, v0
	v_mul_f32_e32 v68, v68, v166
	v_mul_f32_e32 v69, v69, v167
	v_min_f32_e32 v0, 0x7149f2ca, v0
	v_add_f32_e32 v0, 1.0, v0
	v_rcp_f32_e32 v146, v0
	v_and_b32_e32 v0, 0xffff0000, v229
	v_mul_f32_e32 v0, 0xbfb8aa3b, v0
	v_exp_f32_e32 v0, v0
	s_nop 0
	v_min_f32_e32 v3, 0x7149f2ca, v0
	v_and_b32_e32 v0, 0xffff0000, v225
	v_mul_f32_e32 v0, 0xbfb8aa3b, v0
	v_exp_f32_e32 v0, v0
	v_add_f32_e32 v2, 1.0, v2
	v_add_f32_e32 v3, 1.0, v3
	v_min_f32_e32 v0, 0x7149f2ca, v0
	v_add_f32_e32 v0, 1.0, v0
	v_rcp_f32_e32 v147, v0
	v_mov_b32_e32 v0, v155
	v_mul_f32_e32 v2, v2, v146
	v_mul_f32_e32 v3, v3, v147
	s_nop 0
	v_mul_f32_e32 v70, v70, v2
	v_mul_f32_e32 v71, v71, v3
	s_nop 0
	s_nop 0
	v_mad_u64_u32 v[2:3], s[28:29], v0, s30, v[136:137]
	v_mov_b32_e32 v231, 0
	v_bfe_u32 v232, v186, 4, 1
	v_mul_u32_u24_e32 v232, 0x131fc, v232
	v_add_u32_e32 v2, v2, v232
	v_add_u32_e32 v230, s13, v2
	v_lshlrev_b64 v[232:233], 1, v[230:231]
	v_lshl_add_u64 v[198:199], s[4:5], 0, v[232:233]
	v_lshl_add_u64 v[202:203], s[8:9], 0, v[232:233]
	global_load_dwordx4 v[198:201], v[198:199], off
	global_load_dwordx4 v[202:205], v[202:203], off
	v_add_u32_e32 v230, s56, v2
	v_lshlrev_b64 v[232:233], 1, v[230:231]
	v_lshl_add_u64 v[206:207], s[4:5], 0, v[232:233]
	v_lshl_add_u64 v[210:211], s[8:9], 0, v[232:233]
	global_load_dwordx4 v[206:209], v[206:207], off
	global_load_dwordx4 v[210:213], v[210:211], off
	v_add_u32_e32 v230, s57, v2
	v_lshlrev_b64 v[232:233], 1, v[230:231]
	v_lshl_add_u64 v[214:215], s[4:5], 0, v[232:233]
	v_lshl_add_u64 v[218:219], s[8:9], 0, v[232:233]
	global_load_dwordx4 v[214:217], v[214:215], off
	global_load_dwordx4 v[218:221], v[218:219], off
	v_add_u32_e32 v230, s58, v2
	v_lshlrev_b64 v[232:233], 1, v[230:231]
	v_lshl_add_u64 v[222:223], s[4:5], 0, v[232:233]
	v_lshl_add_u64 v[226:227], s[8:9], 0, v[232:233]
	global_load_dwordx4 v[222:225], v[222:223], off
	global_load_dwordx4 v[226:229], v[226:227], off
	s_waitcnt vmcnt(0)
	v_permlane16_swap_b32_e32 v198, v200
	v_permlane16_swap_b32_e32 v199, v201
	v_permlane16_swap_b32_e32 v202, v204
	v_permlane16_swap_b32_e32 v203, v205
	v_permlane16_swap_b32_e32 v206, v208
	v_permlane16_swap_b32_e32 v207, v209
	v_permlane16_swap_b32_e32 v210, v212
	v_permlane16_swap_b32_e32 v211, v213
	v_permlane16_swap_b32_e32 v214, v216
	v_permlane16_swap_b32_e32 v215, v217
	v_permlane16_swap_b32_e32 v218, v220
	v_permlane16_swap_b32_e32 v219, v221
	v_permlane16_swap_b32_e32 v222, v224
	v_permlane16_swap_b32_e32 v223, v225
	v_permlane16_swap_b32_e32 v226, v228
	v_permlane16_swap_b32_e32 v227, v229
	s_nop 1
	v_lshlrev_b32_e32 v0, 16, v202
	v_mul_f32_e32 v0, 0xbfb8aa3b, v0
	v_exp_f32_e32 v0, v0
	s_nop 0
	v_min_f32_e32 v168, 0x7149f2ca, v0
	v_lshlrev_b32_e32 v0, 16, v198
	v_mul_f32_e32 v0, 0xbfb8aa3b, v0
	v_exp_f32_e32 v0, v0
	s_nop 0
	v_min_f32_e32 v0, 0x7149f2ca, v0
	v_add_f32_e32 v0, 1.0, v0
	v_rcp_f32_e32 v170, v0
	v_and_b32_e32 v0, 0xffff0000, v202
	v_mul_f32_e32 v0, 0xbfb8aa3b, v0
	v_exp_f32_e32 v0, v0
	s_nop 0
	v_min_f32_e32 v169, 0x7149f2ca, v0
	v_and_b32_e32 v0, 0xffff0000, v198
	v_mul_f32_e32 v0, 0xbfb8aa3b, v0
	v_exp_f32_e32 v0, v0
	v_add_f32_e32 v168, 1.0, v168
	v_add_f32_e32 v169, 1.0, v169
	v_min_f32_e32 v0, 0x7149f2ca, v0
	v_add_f32_e32 v0, 1.0, v0
	v_rcp_f32_e32 v171, v0
	v_lshlrev_b32_e32 v0, 16, v203
	v_mul_f32_e32 v0, 0xbfb8aa3b, v0
	v_exp_f32_e32 v0, v0
	v_mul_f32_e32 v168, v168, v170
	v_mul_f32_e32 v169, v169, v171
	v_min_f32_e32 v146, 0x7149f2ca, v0
	v_lshlrev_b32_e32 v0, 16, v199
	v_mul_f32_e32 v0, 0xbfb8aa3b, v0
	v_exp_f32_e32 v0, v0
	v_mul_f32_e32 v64, v64, v168
	v_mul_f32_e32 v65, v65, v169
	v_min_f32_e32 v0, 0x7149f2ca, v0
	v_add_f32_e32 v0, 1.0, v0
	v_rcp_f32_e32 v166, v0
	v_and_b32_e32 v0, 0xffff0000, v203
	v_mul_f32_e32 v0, 0xbfb8aa3b, v0
	v_exp_f32_e32 v0, v0
	s_nop 0
	v_min_f32_e32 v147, 0x7149f2ca, v0
	v_and_b32_e32 v0, 0xffff0000, v199
	v_mul_f32_e32 v0, 0xbfb8aa3b, v0
	v_exp_f32_e32 v0, v0
	v_add_f32_e32 v146, 1.0, v146
	v_add_f32_e32 v147, 1.0, v147
	v_min_f32_e32 v0, 0x7149f2ca, v0
	v_add_f32_e32 v0, 1.0, v0
	v_rcp_f32_e32 v167, v0
	s_nop 0
	v_mul_f32_e32 v146, v146, v166
	v_mul_f32_e32 v147, v147, v167
	s_nop 0
	v_mul_f32_e32 v66, v66, v146
	v_mul_f32_e32 v67, v67, v147
	s_nop 0
	s_nop 0
	s_nop 0
	s_waitcnt vmcnt(4)
	v_lshlrev_b32_e32 v0, 16, v210
	v_mul_f32_e32 v0, 0xbfb8aa3b, v0
	v_exp_f32_e32 v0, v0
	s_nop 0
	v_min_f32_e32 v168, 0x7149f2ca, v0
	v_lshlrev_b32_e32 v0, 16, v206
	v_mul_f32_e32 v0, 0xbfb8aa3b, v0
	v_exp_f32_e32 v0, v0
	s_nop 0
	v_min_f32_e32 v0, 0x7149f2ca, v0
	v_add_f32_e32 v0, 1.0, v0
	v_rcp_f32_e32 v170, v0
	v_and_b32_e32 v0, 0xffff0000, v210
	v_mul_f32_e32 v0, 0xbfb8aa3b, v0
	v_exp_f32_e32 v0, v0
	s_nop 0
	v_min_f32_e32 v169, 0x7149f2ca, v0
	v_and_b32_e32 v0, 0xffff0000, v206
	v_mul_f32_e32 v0, 0xbfb8aa3b, v0
	v_exp_f32_e32 v0, v0
	v_add_f32_e32 v168, 1.0, v168
	v_add_f32_e32 v169, 1.0, v169
	v_min_f32_e32 v0, 0x7149f2ca, v0
	v_add_f32_e32 v0, 1.0, v0
	v_rcp_f32_e32 v171, v0
	v_lshlrev_b32_e32 v0, 16, v211
	v_mul_f32_e32 v0, 0xbfb8aa3b, v0
	v_exp_f32_e32 v0, v0
	v_mul_f32_e32 v168, v168, v170
	v_mul_f32_e32 v169, v169, v171
	v_min_f32_e32 v146, 0x7149f2ca, v0
	v_lshlrev_b32_e32 v0, 16, v207
	v_mul_f32_e32 v0, 0xbfb8aa3b, v0
	v_exp_f32_e32 v0, v0
	v_mul_f32_e32 v60, v60, v168
	v_mul_f32_e32 v61, v61, v169
	v_min_f32_e32 v0, 0x7149f2ca, v0
	v_add_f32_e32 v0, 1.0, v0
	v_rcp_f32_e32 v166, v0
	v_and_b32_e32 v0, 0xffff0000, v211
	v_mul_f32_e32 v0, 0xbfb8aa3b, v0
	v_exp_f32_e32 v0, v0
	s_nop 0
	v_min_f32_e32 v147, 0x7149f2ca, v0
	v_and_b32_e32 v0, 0xffff0000, v207
	v_mul_f32_e32 v0, 0xbfb8aa3b, v0
	v_exp_f32_e32 v0, v0
	v_add_f32_e32 v146, 1.0, v146
	v_add_f32_e32 v147, 1.0, v147
	v_min_f32_e32 v0, 0x7149f2ca, v0
	v_add_f32_e32 v0, 1.0, v0
	v_rcp_f32_e32 v167, v0
	s_nop 0
	v_mul_f32_e32 v146, v146, v166
	v_mul_f32_e32 v147, v147, v167
	s_nop 0
	v_mul_f32_e32 v62, v62, v146
	v_mul_f32_e32 v63, v63, v147
	s_nop 0
	s_nop 0
	s_nop 0
	s_waitcnt vmcnt(2)
	v_lshlrev_b32_e32 v0, 16, v218
	v_mul_f32_e32 v0, 0xbfb8aa3b, v0
	v_exp_f32_e32 v0, v0
	s_nop 0
	v_min_f32_e32 v168, 0x7149f2ca, v0
	v_lshlrev_b32_e32 v0, 16, v214
	v_mul_f32_e32 v0, 0xbfb8aa3b, v0
	v_exp_f32_e32 v0, v0
	s_nop 0
	v_min_f32_e32 v0, 0x7149f2ca, v0
	v_add_f32_e32 v0, 1.0, v0
	v_rcp_f32_e32 v170, v0
	v_and_b32_e32 v0, 0xffff0000, v218
	v_mul_f32_e32 v0, 0xbfb8aa3b, v0
	v_exp_f32_e32 v0, v0
	s_nop 0
	v_min_f32_e32 v169, 0x7149f2ca, v0
	v_and_b32_e32 v0, 0xffff0000, v214
	v_mul_f32_e32 v0, 0xbfb8aa3b, v0
	v_exp_f32_e32 v0, v0
	v_add_f32_e32 v168, 1.0, v168
	v_add_f32_e32 v169, 1.0, v169
	v_min_f32_e32 v0, 0x7149f2ca, v0
	v_add_f32_e32 v0, 1.0, v0
	v_rcp_f32_e32 v171, v0
	v_lshlrev_b32_e32 v0, 16, v219
	v_mul_f32_e32 v0, 0xbfb8aa3b, v0
	v_exp_f32_e32 v0, v0
	v_mul_f32_e32 v168, v168, v170
	v_mul_f32_e32 v169, v169, v171
	v_min_f32_e32 v146, 0x7149f2ca, v0
	v_lshlrev_b32_e32 v0, 16, v215
	v_mul_f32_e32 v0, 0xbfb8aa3b, v0
	v_exp_f32_e32 v0, v0
	v_mul_f32_e32 v56, v56, v168
	v_mul_f32_e32 v57, v57, v169
	v_min_f32_e32 v0, 0x7149f2ca, v0
	v_add_f32_e32 v0, 1.0, v0
	v_rcp_f32_e32 v166, v0
	v_and_b32_e32 v0, 0xffff0000, v219
	v_mul_f32_e32 v0, 0xbfb8aa3b, v0
	v_exp_f32_e32 v0, v0
	s_nop 0
	v_min_f32_e32 v147, 0x7149f2ca, v0
	v_and_b32_e32 v0, 0xffff0000, v215
	v_mul_f32_e32 v0, 0xbfb8aa3b, v0
	v_exp_f32_e32 v0, v0
	v_add_f32_e32 v146, 1.0, v146
	v_add_f32_e32 v147, 1.0, v147
	v_min_f32_e32 v0, 0x7149f2ca, v0
	v_add_f32_e32 v0, 1.0, v0
	v_rcp_f32_e32 v167, v0
	s_nop 0
	s_nop 0
	v_mul_f32_e32 v146, v146, v166
	v_mul_f32_e32 v147, v147, v167
	s_nop 0
	v_mul_f32_e32 v58, v58, v146
	v_mul_f32_e32 v59, v59, v147
	s_nop 0
	s_nop 0
	s_waitcnt vmcnt(0)
	v_lshlrev_b32_e32 v0, 16, v226
	v_mul_f32_e32 v0, 0xbfb8aa3b, v0
	v_exp_f32_e32 v0, v0
	s_nop 0
	v_min_f32_e32 v166, 0x7149f2ca, v0
	v_lshlrev_b32_e32 v0, 16, v222
	v_mul_f32_e32 v0, 0xbfb8aa3b, v0
	v_exp_f32_e32 v0, v0
	s_nop 0
	v_min_f32_e32 v0, 0x7149f2ca, v0
	v_add_f32_e32 v0, 1.0, v0
	v_rcp_f32_e32 v168, v0
	v_and_b32_e32 v0, 0xffff0000, v226
	v_mul_f32_e32 v0, 0xbfb8aa3b, v0
	v_exp_f32_e32 v0, v0
	s_nop 0
	v_min_f32_e32 v167, 0x7149f2ca, v0
	v_and_b32_e32 v0, 0xffff0000, v222
	v_mul_f32_e32 v0, 0xbfb8aa3b, v0
	v_exp_f32_e32 v0, v0
	v_add_f32_e32 v166, 1.0, v166
	v_add_f32_e32 v167, 1.0, v167
	v_min_f32_e32 v0, 0x7149f2ca, v0
	v_add_f32_e32 v0, 1.0, v0
	v_rcp_f32_e32 v169, v0
	v_lshlrev_b32_e32 v0, 16, v227
	v_mul_f32_e32 v0, 0xbfb8aa3b, v0
	v_exp_f32_e32 v0, v0
	v_mul_f32_e32 v166, v166, v168
	v_mul_f32_e32 v167, v167, v169
	v_min_f32_e32 v2, 0x7149f2ca, v0
	v_lshlrev_b32_e32 v0, 16, v223
	v_mul_f32_e32 v0, 0xbfb8aa3b, v0
	v_exp_f32_e32 v0, v0
	v_mul_f32_e32 v52, v52, v166
	v_mul_f32_e32 v53, v53, v167
	v_min_f32_e32 v0, 0x7149f2ca, v0
	v_add_f32_e32 v0, 1.0, v0
	v_rcp_f32_e32 v146, v0
	v_and_b32_e32 v0, 0xffff0000, v227
	v_mul_f32_e32 v0, 0xbfb8aa3b, v0
	v_exp_f32_e32 v0, v0
	s_nop 0
	v_min_f32_e32 v3, 0x7149f2ca, v0
	v_and_b32_e32 v0, 0xffff0000, v223
	v_mul_f32_e32 v0, 0xbfb8aa3b, v0
	v_exp_f32_e32 v0, v0
	v_add_f32_e32 v2, 1.0, v2
	v_add_f32_e32 v3, 1.0, v3
	v_min_f32_e32 v0, 0x7149f2ca, v0
	v_add_f32_e32 v0, 1.0, v0
	v_rcp_f32_e32 v147, v0
	v_mov_b32_e32 v0, v156
	v_mul_f32_e32 v2, v2, v146
	v_mul_f32_e32 v3, v3, v147
	s_nop 0
	v_mul_f32_e32 v54, v54, v2
	v_mul_f32_e32 v55, v55, v3
	s_nop 0
	s_nop 0
	v_mad_u64_u32 v[2:3], s[28:29], v0, s30, v[136:137]
	v_lshlrev_b32_e32 v0, 16, v204
	v_mul_f32_e32 v0, 0xbfb8aa3b, v0
	v_exp_f32_e32 v0, v0
	s_nop 0
	v_min_f32_e32 v168, 0x7149f2ca, v0
	v_lshlrev_b32_e32 v0, 16, v200
	v_mul_f32_e32 v0, 0xbfb8aa3b, v0
	v_exp_f32_e32 v0, v0
	s_nop 0
	v_min_f32_e32 v0, 0x7149f2ca, v0
	v_add_f32_e32 v0, 1.0, v0
	v_rcp_f32_e32 v170, v0
	v_and_b32_e32 v0, 0xffff0000, v204
	v_mul_f32_e32 v0, 0xbfb8aa3b, v0
	v_exp_f32_e32 v0, v0
	s_nop 0
	v_min_f32_e32 v169, 0x7149f2ca, v0
	v_and_b32_e32 v0, 0xffff0000, v200
	v_mul_f32_e32 v0, 0xbfb8aa3b, v0
	v_exp_f32_e32 v0, v0
	v_add_f32_e32 v168, 1.0, v168
	v_add_f32_e32 v169, 1.0, v169
	v_min_f32_e32 v0, 0x7149f2ca, v0
	v_add_f32_e32 v0, 1.0, v0
	v_rcp_f32_e32 v171, v0
	v_lshlrev_b32_e32 v0, 16, v205
	v_mul_f32_e32 v0, 0xbfb8aa3b, v0
	v_exp_f32_e32 v0, v0
	v_mul_f32_e32 v168, v168, v170
	v_mul_f32_e32 v169, v169, v171
	v_min_f32_e32 v146, 0x7149f2ca, v0
	v_lshlrev_b32_e32 v0, 16, v201
	v_mul_f32_e32 v0, 0xbfb8aa3b, v0
	v_exp_f32_e32 v0, v0
	v_mul_f32_e32 v48, v48, v168
	v_mul_f32_e32 v49, v49, v169
	v_min_f32_e32 v0, 0x7149f2ca, v0
	v_add_f32_e32 v0, 1.0, v0
	v_rcp_f32_e32 v166, v0
	v_and_b32_e32 v0, 0xffff0000, v205
	v_mul_f32_e32 v0, 0xbfb8aa3b, v0
	v_exp_f32_e32 v0, v0
	s_nop 0
	v_min_f32_e32 v147, 0x7149f2ca, v0
	v_and_b32_e32 v0, 0xffff0000, v201
	v_mul_f32_e32 v0, 0xbfb8aa3b, v0
	v_exp_f32_e32 v0, v0
	v_add_f32_e32 v146, 1.0, v146
	v_add_f32_e32 v147, 1.0, v147
	v_min_f32_e32 v0, 0x7149f2ca, v0
	v_add_f32_e32 v0, 1.0, v0
	v_rcp_f32_e32 v167, v0
	s_nop 0
	v_mul_f32_e32 v146, v146, v166
	v_mul_f32_e32 v147, v147, v167
	s_nop 0
	v_mul_f32_e32 v50, v50, v146
	v_mul_f32_e32 v51, v51, v147
	s_nop 0
	s_nop 0
	s_nop 0
	s_waitcnt vmcnt(4)
	v_lshlrev_b32_e32 v0, 16, v212
	v_mul_f32_e32 v0, 0xbfb8aa3b, v0
	v_exp_f32_e32 v0, v0
	s_nop 0
	v_min_f32_e32 v168, 0x7149f2ca, v0
	v_lshlrev_b32_e32 v0, 16, v208
	v_mul_f32_e32 v0, 0xbfb8aa3b, v0
	v_exp_f32_e32 v0, v0
	s_nop 0
	v_min_f32_e32 v0, 0x7149f2ca, v0
	v_add_f32_e32 v0, 1.0, v0
	v_rcp_f32_e32 v170, v0
	v_and_b32_e32 v0, 0xffff0000, v212
	v_mul_f32_e32 v0, 0xbfb8aa3b, v0
	v_exp_f32_e32 v0, v0
	s_nop 0
	v_min_f32_e32 v169, 0x7149f2ca, v0
	v_and_b32_e32 v0, 0xffff0000, v208
	v_mul_f32_e32 v0, 0xbfb8aa3b, v0
	v_exp_f32_e32 v0, v0
	v_add_f32_e32 v168, 1.0, v168
	v_add_f32_e32 v169, 1.0, v169
	v_min_f32_e32 v0, 0x7149f2ca, v0
	v_add_f32_e32 v0, 1.0, v0
	v_rcp_f32_e32 v171, v0
	v_lshlrev_b32_e32 v0, 16, v213
	v_mul_f32_e32 v0, 0xbfb8aa3b, v0
	v_exp_f32_e32 v0, v0
	v_mul_f32_e32 v168, v168, v170
	v_mul_f32_e32 v169, v169, v171
	v_min_f32_e32 v146, 0x7149f2ca, v0
	v_lshlrev_b32_e32 v0, 16, v209
	v_mul_f32_e32 v0, 0xbfb8aa3b, v0
	v_exp_f32_e32 v0, v0
	v_mul_f32_e32 v44, v44, v168
	v_mul_f32_e32 v45, v45, v169
	v_min_f32_e32 v0, 0x7149f2ca, v0
	v_add_f32_e32 v0, 1.0, v0
	v_rcp_f32_e32 v166, v0
	v_and_b32_e32 v0, 0xffff0000, v213
	v_mul_f32_e32 v0, 0xbfb8aa3b, v0
	v_exp_f32_e32 v0, v0
	s_nop 0
	v_min_f32_e32 v147, 0x7149f2ca, v0
	v_and_b32_e32 v0, 0xffff0000, v209
	v_mul_f32_e32 v0, 0xbfb8aa3b, v0
	v_exp_f32_e32 v0, v0
	v_add_f32_e32 v146, 1.0, v146
	v_add_f32_e32 v147, 1.0, v147
	v_min_f32_e32 v0, 0x7149f2ca, v0
	v_add_f32_e32 v0, 1.0, v0
	v_rcp_f32_e32 v167, v0
	s_nop 0
	v_mul_f32_e32 v146, v146, v166
	v_mul_f32_e32 v147, v147, v167
	s_nop 0
	v_mul_f32_e32 v46, v46, v146
	v_mul_f32_e32 v47, v47, v147
	s_nop 0
	s_nop 0
	s_nop 0
	s_waitcnt vmcnt(2)
	v_lshlrev_b32_e32 v0, 16, v220
	v_mul_f32_e32 v0, 0xbfb8aa3b, v0
	v_exp_f32_e32 v0, v0
	s_nop 0
	v_min_f32_e32 v168, 0x7149f2ca, v0
	v_lshlrev_b32_e32 v0, 16, v216
	v_mul_f32_e32 v0, 0xbfb8aa3b, v0
	v_exp_f32_e32 v0, v0
	s_nop 0
	v_min_f32_e32 v0, 0x7149f2ca, v0
	v_add_f32_e32 v0, 1.0, v0
	v_rcp_f32_e32 v170, v0
	v_and_b32_e32 v0, 0xffff0000, v220
	v_mul_f32_e32 v0, 0xbfb8aa3b, v0
	v_exp_f32_e32 v0, v0
	s_nop 0
	v_min_f32_e32 v169, 0x7149f2ca, v0
	v_and_b32_e32 v0, 0xffff0000, v216
	v_mul_f32_e32 v0, 0xbfb8aa3b, v0
	v_exp_f32_e32 v0, v0
	v_add_f32_e32 v168, 1.0, v168
	v_add_f32_e32 v169, 1.0, v169
	v_min_f32_e32 v0, 0x7149f2ca, v0
	v_add_f32_e32 v0, 1.0, v0
	v_rcp_f32_e32 v171, v0
	v_lshlrev_b32_e32 v0, 16, v221
	v_mul_f32_e32 v0, 0xbfb8aa3b, v0
	v_exp_f32_e32 v0, v0
	v_mul_f32_e32 v168, v168, v170
	v_mul_f32_e32 v169, v169, v171
	v_min_f32_e32 v146, 0x7149f2ca, v0
	v_lshlrev_b32_e32 v0, 16, v217
	v_mul_f32_e32 v0, 0xbfb8aa3b, v0
	v_exp_f32_e32 v0, v0
	v_mul_f32_e32 v40, v40, v168
	v_mul_f32_e32 v41, v41, v169
	v_min_f32_e32 v0, 0x7149f2ca, v0
	v_add_f32_e32 v0, 1.0, v0
	v_rcp_f32_e32 v166, v0
	v_and_b32_e32 v0, 0xffff0000, v221
	v_mul_f32_e32 v0, 0xbfb8aa3b, v0
	v_exp_f32_e32 v0, v0
	s_nop 0
	v_min_f32_e32 v147, 0x7149f2ca, v0
	v_and_b32_e32 v0, 0xffff0000, v217
	v_mul_f32_e32 v0, 0xbfb8aa3b, v0
	v_exp_f32_e32 v0, v0
	v_add_f32_e32 v146, 1.0, v146
	v_add_f32_e32 v147, 1.0, v147
	v_min_f32_e32 v0, 0x7149f2ca, v0
	v_add_f32_e32 v0, 1.0, v0
	v_rcp_f32_e32 v167, v0
	s_nop 0
	s_nop 0
	v_mul_f32_e32 v146, v146, v166
	v_mul_f32_e32 v147, v147, v167
	s_nop 0
	v_mul_f32_e32 v42, v42, v146
	v_mul_f32_e32 v43, v43, v147
	s_nop 0
	s_nop 0
	s_waitcnt vmcnt(0)
	v_lshlrev_b32_e32 v0, 16, v228
	v_mul_f32_e32 v0, 0xbfb8aa3b, v0
	v_exp_f32_e32 v0, v0
	s_nop 0
	v_min_f32_e32 v166, 0x7149f2ca, v0
	v_lshlrev_b32_e32 v0, 16, v224
	v_mul_f32_e32 v0, 0xbfb8aa3b, v0
	v_exp_f32_e32 v0, v0
	s_nop 0
	v_min_f32_e32 v0, 0x7149f2ca, v0
	v_add_f32_e32 v0, 1.0, v0
	v_rcp_f32_e32 v168, v0
	v_and_b32_e32 v0, 0xffff0000, v228
	v_mul_f32_e32 v0, 0xbfb8aa3b, v0
	v_exp_f32_e32 v0, v0
	s_nop 0
	v_min_f32_e32 v167, 0x7149f2ca, v0
	v_and_b32_e32 v0, 0xffff0000, v224
	v_mul_f32_e32 v0, 0xbfb8aa3b, v0
	v_exp_f32_e32 v0, v0
	v_add_f32_e32 v166, 1.0, v166
	v_add_f32_e32 v167, 1.0, v167
	v_min_f32_e32 v0, 0x7149f2ca, v0
	v_add_f32_e32 v0, 1.0, v0
	v_rcp_f32_e32 v169, v0
	v_lshlrev_b32_e32 v0, 16, v229
	v_mul_f32_e32 v0, 0xbfb8aa3b, v0
	v_exp_f32_e32 v0, v0
	v_mul_f32_e32 v166, v166, v168
	v_mul_f32_e32 v167, v167, v169
	v_min_f32_e32 v2, 0x7149f2ca, v0
	v_lshlrev_b32_e32 v0, 16, v225
	v_mul_f32_e32 v0, 0xbfb8aa3b, v0
	v_exp_f32_e32 v0, v0
	v_mul_f32_e32 v36, v36, v166
	v_mul_f32_e32 v37, v37, v167
	v_min_f32_e32 v0, 0x7149f2ca, v0
	v_add_f32_e32 v0, 1.0, v0
	v_rcp_f32_e32 v146, v0
	v_and_b32_e32 v0, 0xffff0000, v229
	v_mul_f32_e32 v0, 0xbfb8aa3b, v0
	v_exp_f32_e32 v0, v0
	s_nop 0
	v_min_f32_e32 v3, 0x7149f2ca, v0
	v_and_b32_e32 v0, 0xffff0000, v225
	v_mul_f32_e32 v0, 0xbfb8aa3b, v0
	v_exp_f32_e32 v0, v0
	v_add_f32_e32 v2, 1.0, v2
	v_add_f32_e32 v3, 1.0, v3
	v_min_f32_e32 v0, 0x7149f2ca, v0
	v_add_f32_e32 v0, 1.0, v0
	v_rcp_f32_e32 v147, v0
	v_mov_b32_e32 v0, v157
	v_mul_f32_e32 v2, v2, v146
	v_mul_f32_e32 v3, v3, v147
	s_nop 0
	v_mul_f32_e32 v38, v38, v2
	v_mul_f32_e32 v39, v39, v3
	s_nop 0
	s_nop 0
	v_mad_u64_u32 v[2:3], s[28:29], v0, s30, v[136:137]
	v_mov_b32_e32 v231, 0
	v_bfe_u32 v232, v186, 4, 1
	v_mul_u32_u24_e32 v232, 0x131fc, v232
	v_add_u32_e32 v2, v2, v232
	v_add_u32_e32 v230, s13, v2
	v_lshlrev_b64 v[232:233], 1, v[230:231]
	v_lshl_add_u64 v[198:199], s[4:5], 0, v[232:233]
	v_lshl_add_u64 v[202:203], s[8:9], 0, v[232:233]
	global_load_dwordx4 v[198:201], v[198:199], off
	global_load_dwordx4 v[202:205], v[202:203], off
	v_add_u32_e32 v230, s56, v2
	v_lshlrev_b64 v[232:233], 1, v[230:231]
	v_lshl_add_u64 v[206:207], s[4:5], 0, v[232:233]
	v_lshl_add_u64 v[210:211], s[8:9], 0, v[232:233]
	global_load_dwordx4 v[206:209], v[206:207], off
	global_load_dwordx4 v[210:213], v[210:211], off
	v_add_u32_e32 v230, s57, v2
	v_lshlrev_b64 v[232:233], 1, v[230:231]
	v_lshl_add_u64 v[214:215], s[4:5], 0, v[232:233]
	v_lshl_add_u64 v[218:219], s[8:9], 0, v[232:233]
	global_load_dwordx4 v[214:217], v[214:215], off
	global_load_dwordx4 v[218:221], v[218:219], off
	v_add_u32_e32 v230, s58, v2
	v_lshlrev_b64 v[232:233], 1, v[230:231]
	v_lshl_add_u64 v[222:223], s[4:5], 0, v[232:233]
	v_lshl_add_u64 v[226:227], s[8:9], 0, v[232:233]
	global_load_dwordx4 v[222:225], v[222:223], off
	global_load_dwordx4 v[226:229], v[226:227], off
	s_waitcnt vmcnt(0)
	v_permlane16_swap_b32_e32 v198, v200
	v_permlane16_swap_b32_e32 v199, v201
	v_permlane16_swap_b32_e32 v202, v204
	v_permlane16_swap_b32_e32 v203, v205
	v_permlane16_swap_b32_e32 v206, v208
	v_permlane16_swap_b32_e32 v207, v209
	v_permlane16_swap_b32_e32 v210, v212
	v_permlane16_swap_b32_e32 v211, v213
	v_permlane16_swap_b32_e32 v214, v216
	v_permlane16_swap_b32_e32 v215, v217
	v_permlane16_swap_b32_e32 v218, v220
	v_permlane16_swap_b32_e32 v219, v221
	v_permlane16_swap_b32_e32 v222, v224
	v_permlane16_swap_b32_e32 v223, v225
	v_permlane16_swap_b32_e32 v226, v228
	v_permlane16_swap_b32_e32 v227, v229
	s_nop 1
	v_lshlrev_b32_e32 v0, 16, v202
	v_mul_f32_e32 v0, 0xbfb8aa3b, v0
	v_exp_f32_e32 v0, v0
	s_nop 0
	v_min_f32_e32 v168, 0x7149f2ca, v0
	v_lshlrev_b32_e32 v0, 16, v198
	v_mul_f32_e32 v0, 0xbfb8aa3b, v0
	v_exp_f32_e32 v0, v0
	s_nop 0
	v_min_f32_e32 v0, 0x7149f2ca, v0
	v_add_f32_e32 v0, 1.0, v0
	v_rcp_f32_e32 v170, v0
	v_and_b32_e32 v0, 0xffff0000, v202
	v_mul_f32_e32 v0, 0xbfb8aa3b, v0
	v_exp_f32_e32 v0, v0
	s_nop 0
	v_min_f32_e32 v169, 0x7149f2ca, v0
	v_and_b32_e32 v0, 0xffff0000, v198
	v_mul_f32_e32 v0, 0xbfb8aa3b, v0
	v_exp_f32_e32 v0, v0
	v_add_f32_e32 v168, 1.0, v168
	v_add_f32_e32 v169, 1.0, v169
	v_min_f32_e32 v0, 0x7149f2ca, v0
	v_add_f32_e32 v0, 1.0, v0
	v_rcp_f32_e32 v171, v0
	v_lshlrev_b32_e32 v0, 16, v203
	v_mul_f32_e32 v0, 0xbfb8aa3b, v0
	v_exp_f32_e32 v0, v0
	v_mul_f32_e32 v168, v168, v170
	v_mul_f32_e32 v169, v169, v171
	v_min_f32_e32 v146, 0x7149f2ca, v0
	v_lshlrev_b32_e32 v0, 16, v199
	v_mul_f32_e32 v0, 0xbfb8aa3b, v0
	v_exp_f32_e32 v0, v0
	v_mul_f32_e32 v32, v32, v168
	v_mul_f32_e32 v33, v33, v169
	v_min_f32_e32 v0, 0x7149f2ca, v0
	v_add_f32_e32 v0, 1.0, v0
	v_rcp_f32_e32 v166, v0
	v_and_b32_e32 v0, 0xffff0000, v203
	v_mul_f32_e32 v0, 0xbfb8aa3b, v0
	v_exp_f32_e32 v0, v0
	s_nop 0
	v_min_f32_e32 v147, 0x7149f2ca, v0
	v_and_b32_e32 v0, 0xffff0000, v199
	v_mul_f32_e32 v0, 0xbfb8aa3b, v0
	v_exp_f32_e32 v0, v0
	v_add_f32_e32 v146, 1.0, v146
	v_add_f32_e32 v147, 1.0, v147
	v_min_f32_e32 v0, 0x7149f2ca, v0
	v_add_f32_e32 v0, 1.0, v0
	v_rcp_f32_e32 v167, v0
	s_nop 0
	v_mul_f32_e32 v146, v146, v166
	v_mul_f32_e32 v147, v147, v167
	s_nop 0
	v_mul_f32_e32 v34, v34, v146
	v_mul_f32_e32 v35, v35, v147
	s_nop 0
	s_nop 0
	s_nop 0
	s_waitcnt vmcnt(4)
	v_lshlrev_b32_e32 v0, 16, v210
	v_mul_f32_e32 v0, 0xbfb8aa3b, v0
	v_exp_f32_e32 v0, v0
	s_nop 0
	v_min_f32_e32 v168, 0x7149f2ca, v0
	v_lshlrev_b32_e32 v0, 16, v206
	v_mul_f32_e32 v0, 0xbfb8aa3b, v0
	v_exp_f32_e32 v0, v0
	s_nop 0
	v_min_f32_e32 v0, 0x7149f2ca, v0
	v_add_f32_e32 v0, 1.0, v0
	v_rcp_f32_e32 v170, v0
	v_and_b32_e32 v0, 0xffff0000, v210
	v_mul_f32_e32 v0, 0xbfb8aa3b, v0
	v_exp_f32_e32 v0, v0
	s_nop 0
	v_min_f32_e32 v169, 0x7149f2ca, v0
	v_and_b32_e32 v0, 0xffff0000, v206
	v_mul_f32_e32 v0, 0xbfb8aa3b, v0
	v_exp_f32_e32 v0, v0
	v_add_f32_e32 v168, 1.0, v168
	v_add_f32_e32 v169, 1.0, v169
	v_min_f32_e32 v0, 0x7149f2ca, v0
	v_add_f32_e32 v0, 1.0, v0
	v_rcp_f32_e32 v171, v0
	v_lshlrev_b32_e32 v0, 16, v211
	v_mul_f32_e32 v0, 0xbfb8aa3b, v0
	v_exp_f32_e32 v0, v0
	v_mul_f32_e32 v168, v168, v170
	v_mul_f32_e32 v169, v169, v171
	v_min_f32_e32 v146, 0x7149f2ca, v0
	v_lshlrev_b32_e32 v0, 16, v207
	v_mul_f32_e32 v0, 0xbfb8aa3b, v0
	v_exp_f32_e32 v0, v0
	v_mul_f32_e32 v28, v28, v168
	v_mul_f32_e32 v29, v29, v169
	v_min_f32_e32 v0, 0x7149f2ca, v0
	v_add_f32_e32 v0, 1.0, v0
	v_rcp_f32_e32 v166, v0
	v_and_b32_e32 v0, 0xffff0000, v211
	v_mul_f32_e32 v0, 0xbfb8aa3b, v0
	v_exp_f32_e32 v0, v0
	s_nop 0
	v_min_f32_e32 v147, 0x7149f2ca, v0
	v_and_b32_e32 v0, 0xffff0000, v207
	v_mul_f32_e32 v0, 0xbfb8aa3b, v0
	v_exp_f32_e32 v0, v0
	v_add_f32_e32 v146, 1.0, v146
	v_add_f32_e32 v147, 1.0, v147
	v_min_f32_e32 v0, 0x7149f2ca, v0
	v_add_f32_e32 v0, 1.0, v0
	v_rcp_f32_e32 v167, v0
	s_nop 0
	v_mul_f32_e32 v146, v146, v166
	v_mul_f32_e32 v147, v147, v167
	s_nop 0
	v_mul_f32_e32 v30, v30, v146
	v_mul_f32_e32 v31, v31, v147
	s_nop 0
	s_nop 0
	s_nop 0
	s_waitcnt vmcnt(2)
	v_lshlrev_b32_e32 v0, 16, v218
	v_mul_f32_e32 v0, 0xbfb8aa3b, v0
	v_exp_f32_e32 v0, v0
	s_nop 0
	v_min_f32_e32 v168, 0x7149f2ca, v0
	v_lshlrev_b32_e32 v0, 16, v214
	v_mul_f32_e32 v0, 0xbfb8aa3b, v0
	v_exp_f32_e32 v0, v0
	s_nop 0
	v_min_f32_e32 v0, 0x7149f2ca, v0
	v_add_f32_e32 v0, 1.0, v0
	v_rcp_f32_e32 v170, v0
	v_and_b32_e32 v0, 0xffff0000, v218
	v_mul_f32_e32 v0, 0xbfb8aa3b, v0
	v_exp_f32_e32 v0, v0
	s_nop 0
	v_min_f32_e32 v169, 0x7149f2ca, v0
	v_and_b32_e32 v0, 0xffff0000, v214
	v_mul_f32_e32 v0, 0xbfb8aa3b, v0
	v_exp_f32_e32 v0, v0
	v_add_f32_e32 v168, 1.0, v168
	v_add_f32_e32 v169, 1.0, v169
	v_min_f32_e32 v0, 0x7149f2ca, v0
	v_add_f32_e32 v0, 1.0, v0
	v_rcp_f32_e32 v171, v0
	v_lshlrev_b32_e32 v0, 16, v219
	v_mul_f32_e32 v0, 0xbfb8aa3b, v0
	v_exp_f32_e32 v0, v0
	v_mul_f32_e32 v168, v168, v170
	v_mul_f32_e32 v169, v169, v171
	v_min_f32_e32 v146, 0x7149f2ca, v0
	v_lshlrev_b32_e32 v0, 16, v215
	v_mul_f32_e32 v0, 0xbfb8aa3b, v0
	v_exp_f32_e32 v0, v0
	v_mul_f32_e32 v24, v24, v168
	v_mul_f32_e32 v25, v25, v169
	v_min_f32_e32 v0, 0x7149f2ca, v0
	v_add_f32_e32 v0, 1.0, v0
	v_rcp_f32_e32 v166, v0
	v_and_b32_e32 v0, 0xffff0000, v219
	v_mul_f32_e32 v0, 0xbfb8aa3b, v0
	v_exp_f32_e32 v0, v0
	s_nop 0
	v_min_f32_e32 v147, 0x7149f2ca, v0
	v_and_b32_e32 v0, 0xffff0000, v215
	v_mul_f32_e32 v0, 0xbfb8aa3b, v0
	v_exp_f32_e32 v0, v0
	v_add_f32_e32 v146, 1.0, v146
	v_add_f32_e32 v147, 1.0, v147
	v_min_f32_e32 v0, 0x7149f2ca, v0
	v_add_f32_e32 v0, 1.0, v0
	v_rcp_f32_e32 v167, v0
	s_nop 0
	s_nop 0
	v_mul_f32_e32 v146, v146, v166
	v_mul_f32_e32 v147, v147, v167
	s_nop 0
	v_mul_f32_e32 v26, v26, v146
	v_mul_f32_e32 v27, v27, v147
	s_nop 0
	s_nop 0
	s_waitcnt vmcnt(0)
	v_lshlrev_b32_e32 v0, 16, v226
	v_mul_f32_e32 v0, 0xbfb8aa3b, v0
	v_exp_f32_e32 v0, v0
	s_nop 0
	v_min_f32_e32 v166, 0x7149f2ca, v0
	v_lshlrev_b32_e32 v0, 16, v222
	v_mul_f32_e32 v0, 0xbfb8aa3b, v0
	v_exp_f32_e32 v0, v0
	s_nop 0
	v_min_f32_e32 v0, 0x7149f2ca, v0
	v_add_f32_e32 v0, 1.0, v0
	v_rcp_f32_e32 v168, v0
	v_and_b32_e32 v0, 0xffff0000, v226
	v_mul_f32_e32 v0, 0xbfb8aa3b, v0
	v_exp_f32_e32 v0, v0
	s_nop 0
	v_min_f32_e32 v167, 0x7149f2ca, v0
	v_and_b32_e32 v0, 0xffff0000, v222
	v_mul_f32_e32 v0, 0xbfb8aa3b, v0
	v_exp_f32_e32 v0, v0
	v_add_f32_e32 v166, 1.0, v166
	v_add_f32_e32 v167, 1.0, v167
	v_min_f32_e32 v0, 0x7149f2ca, v0
	v_add_f32_e32 v0, 1.0, v0
	v_rcp_f32_e32 v169, v0
	v_lshlrev_b32_e32 v0, 16, v227
	v_mul_f32_e32 v0, 0xbfb8aa3b, v0
	v_exp_f32_e32 v0, v0
	v_mul_f32_e32 v166, v166, v168
	v_mul_f32_e32 v167, v167, v169
	v_min_f32_e32 v2, 0x7149f2ca, v0
	v_lshlrev_b32_e32 v0, 16, v223
	v_mul_f32_e32 v0, 0xbfb8aa3b, v0
	v_exp_f32_e32 v0, v0
	v_mul_f32_e32 v20, v20, v166
	v_mul_f32_e32 v21, v21, v167
	v_min_f32_e32 v0, 0x7149f2ca, v0
	v_add_f32_e32 v0, 1.0, v0
	v_rcp_f32_e32 v146, v0
	v_and_b32_e32 v0, 0xffff0000, v227
	v_mul_f32_e32 v0, 0xbfb8aa3b, v0
	v_exp_f32_e32 v0, v0
	s_nop 0
	v_min_f32_e32 v3, 0x7149f2ca, v0
	v_and_b32_e32 v0, 0xffff0000, v223
	v_mul_f32_e32 v0, 0xbfb8aa3b, v0
	v_exp_f32_e32 v0, v0
	v_add_f32_e32 v2, 1.0, v2
	v_add_f32_e32 v3, 1.0, v3
	v_min_f32_e32 v0, 0x7149f2ca, v0
	v_add_f32_e32 v0, 1.0, v0
	v_rcp_f32_e32 v147, v0
	v_mov_b32_e32 v0, v158
	v_mul_f32_e32 v2, v2, v146
	v_mul_f32_e32 v3, v3, v147
	s_nop 0
	v_mul_f32_e32 v22, v22, v2
	v_mul_f32_e32 v23, v23, v3
	s_nop 0
	s_nop 0
	v_mad_u64_u32 v[2:3], s[28:29], v0, s30, v[136:137]
	v_lshlrev_b32_e32 v0, 16, v204
	v_mul_f32_e32 v0, 0xbfb8aa3b, v0
	v_exp_f32_e32 v0, v0
	s_nop 0
	v_min_f32_e32 v168, 0x7149f2ca, v0
	v_lshlrev_b32_e32 v0, 16, v200
	v_mul_f32_e32 v0, 0xbfb8aa3b, v0
	v_exp_f32_e32 v0, v0
	s_nop 0
	v_min_f32_e32 v0, 0x7149f2ca, v0
	v_add_f32_e32 v0, 1.0, v0
	v_rcp_f32_e32 v170, v0
	v_and_b32_e32 v0, 0xffff0000, v204
	v_mul_f32_e32 v0, 0xbfb8aa3b, v0
	v_exp_f32_e32 v0, v0
	s_nop 0
	v_min_f32_e32 v169, 0x7149f2ca, v0
	v_and_b32_e32 v0, 0xffff0000, v200
	v_mul_f32_e32 v0, 0xbfb8aa3b, v0
	v_exp_f32_e32 v0, v0
	v_add_f32_e32 v168, 1.0, v168
	v_add_f32_e32 v169, 1.0, v169
	v_min_f32_e32 v0, 0x7149f2ca, v0
	v_add_f32_e32 v0, 1.0, v0
	v_rcp_f32_e32 v171, v0
	v_lshlrev_b32_e32 v0, 16, v205
	v_mul_f32_e32 v0, 0xbfb8aa3b, v0
	v_exp_f32_e32 v0, v0
	v_mul_f32_e32 v168, v168, v170
	v_mul_f32_e32 v169, v169, v171
	v_min_f32_e32 v146, 0x7149f2ca, v0
	v_lshlrev_b32_e32 v0, 16, v201
	v_mul_f32_e32 v0, 0xbfb8aa3b, v0
	v_exp_f32_e32 v0, v0
	v_mul_f32_e32 v16, v16, v168
	v_mul_f32_e32 v17, v17, v169
	v_min_f32_e32 v0, 0x7149f2ca, v0
	v_add_f32_e32 v0, 1.0, v0
	v_rcp_f32_e32 v166, v0
	v_and_b32_e32 v0, 0xffff0000, v205
	v_mul_f32_e32 v0, 0xbfb8aa3b, v0
	v_exp_f32_e32 v0, v0
	s_nop 0
	v_min_f32_e32 v147, 0x7149f2ca, v0
	v_and_b32_e32 v0, 0xffff0000, v201
	v_mul_f32_e32 v0, 0xbfb8aa3b, v0
	v_exp_f32_e32 v0, v0
	v_add_f32_e32 v146, 1.0, v146
	v_add_f32_e32 v147, 1.0, v147
	v_min_f32_e32 v0, 0x7149f2ca, v0
	v_add_f32_e32 v0, 1.0, v0
	v_rcp_f32_e32 v167, v0
	s_nop 0
	v_mul_f32_e32 v146, v146, v166
	v_mul_f32_e32 v147, v147, v167
	s_nop 0
	v_mul_f32_e32 v18, v18, v146
	v_mul_f32_e32 v19, v19, v147
	s_nop 0
	s_nop 0
	s_nop 0
	s_waitcnt vmcnt(4)
	v_lshlrev_b32_e32 v0, 16, v212
	v_mul_f32_e32 v0, 0xbfb8aa3b, v0
	v_exp_f32_e32 v0, v0
	s_nop 0
	v_min_f32_e32 v168, 0x7149f2ca, v0
	v_lshlrev_b32_e32 v0, 16, v208
	v_mul_f32_e32 v0, 0xbfb8aa3b, v0
	v_exp_f32_e32 v0, v0
	s_nop 0
	v_min_f32_e32 v0, 0x7149f2ca, v0
	v_add_f32_e32 v0, 1.0, v0
	v_rcp_f32_e32 v170, v0
	v_and_b32_e32 v0, 0xffff0000, v212
	v_mul_f32_e32 v0, 0xbfb8aa3b, v0
	v_exp_f32_e32 v0, v0
	s_nop 0
	v_min_f32_e32 v169, 0x7149f2ca, v0
	v_and_b32_e32 v0, 0xffff0000, v208
	v_mul_f32_e32 v0, 0xbfb8aa3b, v0
	v_exp_f32_e32 v0, v0
	v_add_f32_e32 v168, 1.0, v168
	v_add_f32_e32 v169, 1.0, v169
	v_min_f32_e32 v0, 0x7149f2ca, v0
	v_add_f32_e32 v0, 1.0, v0
	v_rcp_f32_e32 v171, v0
	v_lshlrev_b32_e32 v0, 16, v213
	v_mul_f32_e32 v0, 0xbfb8aa3b, v0
	v_exp_f32_e32 v0, v0
	v_mul_f32_e32 v168, v168, v170
	v_mul_f32_e32 v169, v169, v171
	v_min_f32_e32 v146, 0x7149f2ca, v0
	v_lshlrev_b32_e32 v0, 16, v209
	v_mul_f32_e32 v0, 0xbfb8aa3b, v0
	v_exp_f32_e32 v0, v0
	v_mul_f32_e32 v12, v12, v168
	v_mul_f32_e32 v13, v13, v169
	v_min_f32_e32 v0, 0x7149f2ca, v0
	v_add_f32_e32 v0, 1.0, v0
	v_rcp_f32_e32 v166, v0
	v_and_b32_e32 v0, 0xffff0000, v213
	v_mul_f32_e32 v0, 0xbfb8aa3b, v0
	v_exp_f32_e32 v0, v0
	s_nop 0
	v_min_f32_e32 v147, 0x7149f2ca, v0
	v_and_b32_e32 v0, 0xffff0000, v209
	v_mul_f32_e32 v0, 0xbfb8aa3b, v0
	v_exp_f32_e32 v0, v0
	v_add_f32_e32 v146, 1.0, v146
	v_add_f32_e32 v147, 1.0, v147
	v_min_f32_e32 v0, 0x7149f2ca, v0
	v_add_f32_e32 v0, 1.0, v0
	v_rcp_f32_e32 v167, v0
	s_nop 0
	v_mul_f32_e32 v146, v146, v166
	v_mul_f32_e32 v147, v147, v167
	s_nop 0
	v_mul_f32_e32 v14, v14, v146
	v_mul_f32_e32 v15, v15, v147
	s_nop 0
	s_nop 0
	s_nop 0
	s_waitcnt vmcnt(2)
	v_lshlrev_b32_e32 v0, 16, v220
	v_mul_f32_e32 v0, 0xbfb8aa3b, v0
	v_exp_f32_e32 v0, v0
	s_nop 0
	v_min_f32_e32 v168, 0x7149f2ca, v0
	v_lshlrev_b32_e32 v0, 16, v216
	v_mul_f32_e32 v0, 0xbfb8aa3b, v0
	v_exp_f32_e32 v0, v0
	s_nop 0
	v_min_f32_e32 v0, 0x7149f2ca, v0
	v_add_f32_e32 v0, 1.0, v0
	v_rcp_f32_e32 v170, v0
	v_and_b32_e32 v0, 0xffff0000, v220
	v_mul_f32_e32 v0, 0xbfb8aa3b, v0
	v_exp_f32_e32 v0, v0
	s_nop 0
	v_min_f32_e32 v169, 0x7149f2ca, v0
	v_and_b32_e32 v0, 0xffff0000, v216
	v_mul_f32_e32 v0, 0xbfb8aa3b, v0
	v_exp_f32_e32 v0, v0
	v_add_f32_e32 v168, 1.0, v168
	v_add_f32_e32 v169, 1.0, v169
	v_min_f32_e32 v0, 0x7149f2ca, v0
	v_add_f32_e32 v0, 1.0, v0
	v_rcp_f32_e32 v171, v0
	v_lshlrev_b32_e32 v0, 16, v221
	v_mul_f32_e32 v0, 0xbfb8aa3b, v0
	v_exp_f32_e32 v0, v0
	v_mul_f32_e32 v168, v168, v170
	v_mul_f32_e32 v169, v169, v171
	v_min_f32_e32 v146, 0x7149f2ca, v0
	v_lshlrev_b32_e32 v0, 16, v217
	v_mul_f32_e32 v0, 0xbfb8aa3b, v0
	v_exp_f32_e32 v0, v0
	v_mul_f32_e32 v8, v8, v168
	v_mul_f32_e32 v9, v9, v169
	v_min_f32_e32 v0, 0x7149f2ca, v0
	v_add_f32_e32 v0, 1.0, v0
	v_rcp_f32_e32 v166, v0
	v_and_b32_e32 v0, 0xffff0000, v221
	v_mul_f32_e32 v0, 0xbfb8aa3b, v0
	v_exp_f32_e32 v0, v0
	s_nop 0
	v_min_f32_e32 v147, 0x7149f2ca, v0
	v_and_b32_e32 v0, 0xffff0000, v217
	v_mul_f32_e32 v0, 0xbfb8aa3b, v0
	v_exp_f32_e32 v0, v0
	v_add_f32_e32 v146, 1.0, v146
	v_add_f32_e32 v147, 1.0, v147
	v_min_f32_e32 v0, 0x7149f2ca, v0
	v_add_f32_e32 v0, 1.0, v0
	v_rcp_f32_e32 v167, v0
	s_nop 0
	v_mul_f32_e32 v146, v146, v166
	v_mul_f32_e32 v147, v147, v167
	s_nop 0
	v_mul_f32_e32 v10, v10, v146
	v_mul_f32_e32 v11, v11, v147
	s_nop 0
	s_nop 0
	s_nop 0
	s_waitcnt vmcnt(0)
	v_lshlrev_b32_e32 v0, 16, v228
	v_mul_f32_e32 v0, 0xbfb8aa3b, v0
	v_exp_f32_e32 v0, v0
	s_nop 0
	v_min_f32_e32 v146, 0x7149f2ca, v0
	v_lshlrev_b32_e32 v0, 16, v224
	v_mul_f32_e32 v0, 0xbfb8aa3b, v0
	v_exp_f32_e32 v0, v0
	s_nop 0
	v_min_f32_e32 v0, 0x7149f2ca, v0
	v_add_f32_e32 v0, 1.0, v0
	v_rcp_f32_e32 v168, v0
	v_and_b32_e32 v0, 0xffff0000, v228
	v_mul_f32_e32 v0, 0xbfb8aa3b, v0
	v_exp_f32_e32 v0, v0
	s_nop 0
	v_min_f32_e32 v147, 0x7149f2ca, v0
	v_and_b32_e32 v0, 0xffff0000, v224
	v_mul_f32_e32 v0, 0xbfb8aa3b, v0
	v_exp_f32_e32 v0, v0
	v_add_f32_e32 v146, 1.0, v146
	v_add_f32_e32 v147, 1.0, v147
	v_min_f32_e32 v0, 0x7149f2ca, v0
	v_add_f32_e32 v0, 1.0, v0
	v_rcp_f32_e32 v169, v0
	v_lshlrev_b32_e32 v0, 16, v229
	v_mul_f32_e32 v0, 0xbfb8aa3b, v0
	v_exp_f32_e32 v0, v0
	v_mul_f32_e32 v146, v146, v168
	v_mul_f32_e32 v147, v147, v169
	v_min_f32_e32 v166, 0x7149f2ca, v0
	v_lshlrev_b32_e32 v0, 16, v225
	v_mul_f32_e32 v0, 0xbfb8aa3b, v0
	v_exp_f32_e32 v0, v0
	v_mul_f32_e32 v4, v4, v146
	v_mul_f32_e32 v5, v5, v147
	v_min_f32_e32 v0, 0x7149f2ca, v0
	v_add_f32_e32 v0, 1.0, v0
	v_rcp_f32_e32 v2, v0
	v_and_b32_e32 v0, 0xffff0000, v229
	v_mul_f32_e32 v0, 0xbfb8aa3b, v0
	v_exp_f32_e32 v0, v0
	s_nop 0
	v_min_f32_e32 v167, 0x7149f2ca, v0
	v_and_b32_e32 v0, 0xffff0000, v225
	v_mul_f32_e32 v0, 0xbfb8aa3b, v0
	v_exp_f32_e32 v0, v0
	v_add_f32_e32 v166, 1.0, v166
	v_add_f32_e32 v167, 1.0, v167
	v_min_f32_e32 v0, 0x7149f2ca, v0
	v_add_f32_e32 v0, 1.0, v0
	v_rcp_f32_e32 v3, v0
	s_nop 0
	v_mul_f32_e32 v2, v166, v2
	v_mul_f32_e32 v3, v167, v3
	s_nop 0
	v_mul_f32_e32 v6, v6, v2
	v_mul_f32_e32 v7, v7, v3
	s_nop 0
